# v020 + mixer-in exact-gelu epilogue blocks regenerated: same A&S erf arithmetic, abs via VOP3 modifier, result = fma(-|v|, q*e, max(v,0)) instead of mul+fma+cmp+cndmask, two pairs interleaved (no s_no
# speedup vs baseline: 1.0145x; 1.0046x over previous
; __device__ __forceinline__ unsigned pk_bf16(float lo, float hi) { f32x2 v = {lo, hi}; bf16x2_t b = __builtin_convertvector(v, bf16x2_t); return __builtin_bit_cast(unsigned, b); }
; __device__ __forceinline__ f32x4 gelu4(f32x4 v) { f32x2 a = gelu_pk((f32x2){v[0], v[1]}), b = gelu_pk((f32x2){v[2], v[3]}); return (f32x4){a.x, a.y, b.x, b.y}; }
; __device__ __forceinline__ f32x2 gelu_pk(f32x2 v) {
;     const f32x2 av = __builtin_elementwise_abs(v), d = av * 0.2316418882f + 1.0f;
;     f32x2 t; t.x = __builtin_amdgcn_rcpf(d.x); t.y = __builtin_amdgcn_rcpf(d.y);
;     f32x2 q = t * 0.5307027145f + (-0.7265760135f); q = q * t + 0.7107068705f; q = q * t + (-0.142248368f); q = q * t + 0.127414796f; q = q * t;
;     const f32x2 s = (v * v) * (-0.72134752044f);
;     f32x2 e; e.x = __builtin_amdgcn_exp2f(s.x); e.y = __builtin_amdgcn_exp2f(s.y);
;     const f32x2 m = v * (q * e), r = v - m;
;     f32x2 o; o.x = v.x < 0.f ? m.x : r.x; o.y = v.y < 0.f ? m.y : r.y; return o;
;     __device__ __forceinline__ void operator()(const f32x4 (&acc)[2][2][4][2], const Unit& u, int wr, int wc, int fr, int fq, float rp0, float rp1, const f32x4& raw0, const f32x4& raw1, float& rn0, float& rn1) const {
;     ...
;             const bool gel = mode == 1;
; #pragma unroll
;             for (int ai = 0; ai < 2; ++ai) {
;                 float rs[4];
; #pragma unroll
;                 for (int k = 0; k < 4; ++k) rs[k] = __shfl(ai ? rp1 : rp0, fr + 16 * k);
; #pragma unroll
;                 for (int m = 0; m < 4; ++m) {
;                     const int roff = ai * HALF + m * 16; const float r = rs[m];
; #pragma unroll
;                     for (int bj = 0; bj < 2; ++bj) {
;                         f32x4 v0 = acc[ai][bj][m][0] * r, v1 = acc[ai][bj][m][1] * r;
;                         if (gel) { v0 = gelu4(v0); v1 = gelu4(v1); }
;                         u32x4 w; w.x = pk_bf16(v0[0], v0[1]); w.y = pk_bf16(v0[2], v0[3]); w.z = pk_bf16(v1[0], v1[1]); w.w = pk_bf16(v1[2], v1[3]);
.LBB0_131:
	v_lshl_add_u64 v[156:157], v[138:139], 0, v[0:1]
	s_mov_b64 s[42:43], -1
	s_and_b64 vcc, exec, s[6:7]
	s_mul_i32 s2, s10, 0x160
	s_cbranch_vccnz .LBB0_165
	v_and_or_b32 v138, v197, 64, v173
	v_lshlrev_b32_e32 v170, 2, v138
	ds_bpermute_b32 v160, v170, v155
	ds_bpermute_b32 v158, v170, v155 offset:64
	ds_bpermute_b32 v140, v170, v155 offset:128
	ds_bpermute_b32 v138, v170, v155 offset:192
	s_and_b64 vcc, exec, s[40:41]
	s_waitcnt lgkmcnt(0)
	v_pk_mul_f32 v[162:163], v[116:117], v[160:161] op_sel_hi:[1,0]
	v_pk_mul_f32 v[164:165], v[114:115], v[160:161] op_sel_hi:[1,0]
	v_pk_mul_f32 v[166:167], v[120:121], v[160:161] op_sel_hi:[1,0]
	v_pk_mul_f32 v[168:169], v[118:119], v[160:161] op_sel_hi:[1,0]
	s_cbranch_vccz .LBB0_134
	v_mov_b32_e32 v232, s68
	v_fma_f32 v220, |v164|, s88, 1.0
	v_fma_f32 v221, |v165|, s88, 1.0
	v_fma_f32 v226, |v162|, s88, 1.0
	v_fma_f32 v227, |v163|, s88, 1.0
	v_pk_mul_f32 v[224:225], v[164:165], v[164:165]
	v_pk_mul_f32 v[230:231], v[162:163], v[162:163]
	v_rcp_f32_e32 v220, v220
	v_rcp_f32_e32 v221, v221
	v_rcp_f32_e32 v226, v226
	v_rcp_f32_e32 v227, v227
	v_pk_mul_f32 v[224:225], v[224:225], s[72:73] op_sel_hi:[1,0]
	v_pk_mul_f32 v[230:231], v[230:231], s[72:73] op_sel_hi:[1,0]
	v_pk_fma_f32 v[222:223], v[220:221], s[90:91], v[232:233] op_sel_hi:[1,0,0]
	v_pk_fma_f32 v[228:229], v[226:227], s[90:91], v[232:233] op_sel_hi:[1,0,0]
	v_exp_f32_e32 v224, v224
	v_exp_f32_e32 v225, v225
	v_exp_f32_e32 v230, v230
	v_exp_f32_e32 v231, v231
	v_pk_fma_f32 v[222:223], v[220:221], v[222:223], s[94:95] op_sel_hi:[1,1,0]
	v_pk_fma_f32 v[228:229], v[226:227], v[228:229], s[94:95] op_sel_hi:[1,1,0]
	v_pk_fma_f32 v[222:223], v[220:221], v[222:223], s[96:97] op_sel_hi:[1,1,0]
	v_pk_fma_f32 v[228:229], v[226:227], v[228:229], s[96:97] op_sel_hi:[1,1,0]
	v_pk_fma_f32 v[222:223], v[220:221], v[222:223], s[98:99] op_sel_hi:[1,1,0]
	v_pk_fma_f32 v[228:229], v[226:227], v[228:229], s[98:99] op_sel_hi:[1,1,0]
	v_pk_mul_f32 v[222:223], v[220:221], v[222:223]
	v_pk_mul_f32 v[228:229], v[226:227], v[228:229]
	v_pk_mul_f32 v[222:223], v[224:225], v[222:223]
	v_pk_mul_f32 v[228:229], v[230:231], v[228:229]
	v_max_f32_e32 v220, 0, v164
	v_max_f32_e32 v221, 0, v165
	v_max_f32_e32 v226, 0, v162
	v_max_f32_e32 v227, 0, v163
	v_fma_f32 v164, -|v164|, v222, v220
	v_fma_f32 v165, -|v165|, v223, v221
	v_fma_f32 v162, -|v162|, v228, v226
	v_fma_f32 v163, -|v163|, v229, v227
	v_fma_f32 v220, |v168|, s88, 1.0
	v_fma_f32 v221, |v169|, s88, 1.0
	v_fma_f32 v226, |v166|, s88, 1.0
	v_fma_f32 v227, |v167|, s88, 1.0
	v_pk_mul_f32 v[224:225], v[168:169], v[168:169]
	v_pk_mul_f32 v[230:231], v[166:167], v[166:167]
	v_rcp_f32_e32 v220, v220
	v_rcp_f32_e32 v221, v221
	v_rcp_f32_e32 v226, v226
	v_rcp_f32_e32 v227, v227
	v_pk_mul_f32 v[224:225], v[224:225], s[72:73] op_sel_hi:[1,0]
	v_pk_mul_f32 v[230:231], v[230:231], s[72:73] op_sel_hi:[1,0]
	v_pk_fma_f32 v[222:223], v[220:221], s[90:91], v[232:233] op_sel_hi:[1,0,0]
	v_pk_fma_f32 v[228:229], v[226:227], s[90:91], v[232:233] op_sel_hi:[1,0,0]
	v_exp_f32_e32 v224, v224
	v_exp_f32_e32 v225, v225
	v_exp_f32_e32 v230, v230
	v_exp_f32_e32 v231, v231
	v_pk_fma_f32 v[222:223], v[220:221], v[222:223], s[94:95] op_sel_hi:[1,1,0]
	v_pk_fma_f32 v[228:229], v[226:227], v[228:229], s[94:95] op_sel_hi:[1,1,0]
	v_pk_fma_f32 v[222:223], v[220:221], v[222:223], s[96:97] op_sel_hi:[1,1,0]
	v_pk_fma_f32 v[228:229], v[226:227], v[228:229], s[96:97] op_sel_hi:[1,1,0]
	v_pk_fma_f32 v[222:223], v[220:221], v[222:223], s[98:99] op_sel_hi:[1,1,0]
	v_pk_fma_f32 v[228:229], v[226:227], v[228:229], s[98:99] op_sel_hi:[1,1,0]
	v_pk_mul_f32 v[222:223], v[220:221], v[222:223]
	v_pk_mul_f32 v[228:229], v[226:227], v[228:229]
	v_pk_mul_f32 v[222:223], v[224:225], v[222:223]
	v_pk_mul_f32 v[228:229], v[230:231], v[228:229]
	v_max_f32_e32 v220, 0, v168
	v_max_f32_e32 v221, 0, v169
	v_max_f32_e32 v226, 0, v166
	v_max_f32_e32 v227, 0, v167
	v_fma_f32 v168, -|v168|, v222, v220
	v_fma_f32 v169, -|v169|, v223, v221
	v_fma_f32 v166, -|v166|, v228, v226
	v_fma_f32 v167, -|v167|, v229, v227
.LBB0_134:
	v_mov_b32_e32 v161, v160
	v_cvt_pk_bf16_f32 v177, v166, v167
	v_mov_b32_e32 v166, v160
	v_mov_b32_e32 v167, v160
	v_cndmask_b32_e64 v139, 0, 1, s[40:41]
	v_cvt_pk_bf16_f32 v174, v164, v165
	v_cvt_pk_bf16_f32 v175, v162, v163
	v_cvt_pk_bf16_f32 v176, v168, v169
	v_pk_mul_f32 v[162:163], v[124:125], v[166:167]
	v_pk_mul_f32 v[164:165], v[122:123], v[160:161]
	v_pk_mul_f32 v[166:167], v[128:129], v[166:167]
	v_cmp_ne_u32_e64 s[6:7], 1, v139
	s_andn2_b64 vcc, exec, s[40:41]
	v_pk_mul_f32 v[160:161], v[126:127], v[160:161]
	global_store_dwordx4 v[156:157], v[174:177], off
	s_cbranch_vccnz .LBB0_136
; __device__ __forceinline__ unsigned pk_bf16(float lo, float hi) { f32x2 v = {lo, hi}; bf16x2_t b = __builtin_convertvector(v, bf16x2_t); return __builtin_bit_cast(unsigned, b); }
; __device__ __forceinline__ f32x4 gelu4(f32x4 v) { f32x2 a = gelu_pk((f32x2){v[0], v[1]}), b = gelu_pk((f32x2){v[2], v[3]}); return (f32x4){a.x, a.y, b.x, b.y}; }
; __device__ __forceinline__ f32x2 gelu_pk(f32x2 v) {
;     const f32x2 av = __builtin_elementwise_abs(v), d = av * 0.2316418882f + 1.0f;
;     f32x2 t; t.x = __builtin_amdgcn_rcpf(d.x); t.y = __builtin_amdgcn_rcpf(d.y);
;     f32x2 q = t * 0.5307027145f + (-0.7265760135f); q = q * t + 0.7107068705f; q = q * t + (-0.142248368f); q = q * t + 0.127414796f; q = q * t;
;     const f32x2 s = (v * v) * (-0.72134752044f);
;     f32x2 e; e.x = __builtin_amdgcn_exp2f(s.x); e.y = __builtin_amdgcn_exp2f(s.y);
;     const f32x2 m = v * (q * e), r = v - m;
;     f32x2 o; o.x = v.x < 0.f ? m.x : r.x; o.y = v.y < 0.f ? m.y : r.y; return o;
;     __device__ __forceinline__ void operator()(const f32x4 (&acc)[2][2][4][2], const Unit& u, int wr, int wc, int fr, int fq, float rp0, float rp1, const f32x4& raw0, const f32x4& raw1, float& rn0, float& rn1) const {
;     ...
;                         f32x4 v0 = acc[ai][bj][m][0] * r, v1 = acc[ai][bj][m][1] * r;
;                         if (gel) { v0 = gelu4(v0); v1 = gelu4(v1); }
;                         u32x4 w; w.x = pk_bf16(v0[0], v0[1]); w.y = pk_bf16(v0[2], v0[3]); w.z = pk_bf16(v1[0], v1[1]); w.w = pk_bf16(v1[2], v1[3]);
;                         *(u32x4*)(base + (size_t)roff * ld + bj * 32) = w;
	v_mov_b32_e32 v232, s68
	v_fma_f32 v220, |v164|, s88, 1.0
	v_fma_f32 v221, |v165|, s88, 1.0
	v_fma_f32 v226, |v162|, s88, 1.0
	v_fma_f32 v227, |v163|, s88, 1.0
	v_pk_mul_f32 v[224:225], v[164:165], v[164:165]
	v_pk_mul_f32 v[230:231], v[162:163], v[162:163]
	v_rcp_f32_e32 v220, v220
	v_rcp_f32_e32 v221, v221
	v_rcp_f32_e32 v226, v226
	v_rcp_f32_e32 v227, v227
	v_pk_mul_f32 v[224:225], v[224:225], s[72:73] op_sel_hi:[1,0]
	v_pk_mul_f32 v[230:231], v[230:231], s[72:73] op_sel_hi:[1,0]
	v_pk_fma_f32 v[222:223], v[220:221], s[90:91], v[232:233] op_sel_hi:[1,0,0]
	v_pk_fma_f32 v[228:229], v[226:227], s[90:91], v[232:233] op_sel_hi:[1,0,0]
	v_exp_f32_e32 v224, v224
	v_exp_f32_e32 v225, v225
	v_exp_f32_e32 v230, v230
	v_exp_f32_e32 v231, v231
	v_pk_fma_f32 v[222:223], v[220:221], v[222:223], s[94:95] op_sel_hi:[1,1,0]
	v_pk_fma_f32 v[228:229], v[226:227], v[228:229], s[94:95] op_sel_hi:[1,1,0]
	v_pk_fma_f32 v[222:223], v[220:221], v[222:223], s[96:97] op_sel_hi:[1,1,0]
	v_pk_fma_f32 v[228:229], v[226:227], v[228:229], s[96:97] op_sel_hi:[1,1,0]
	v_pk_fma_f32 v[222:223], v[220:221], v[222:223], s[98:99] op_sel_hi:[1,1,0]
	v_pk_fma_f32 v[228:229], v[226:227], v[228:229], s[98:99] op_sel_hi:[1,1,0]
	v_pk_mul_f32 v[222:223], v[220:221], v[222:223]
	v_pk_mul_f32 v[228:229], v[226:227], v[228:229]
	v_pk_mul_f32 v[222:223], v[224:225], v[222:223]
	v_pk_mul_f32 v[228:229], v[230:231], v[228:229]
	v_max_f32_e32 v220, 0, v164
	v_max_f32_e32 v221, 0, v165
	v_max_f32_e32 v226, 0, v162
	v_max_f32_e32 v227, 0, v163
	v_fma_f32 v164, -|v164|, v222, v220
	v_fma_f32 v165, -|v165|, v223, v221
	v_fma_f32 v162, -|v162|, v228, v226
	v_fma_f32 v163, -|v163|, v229, v227
	v_fma_f32 v220, |v160|, s88, 1.0
	v_fma_f32 v221, |v161|, s88, 1.0
	v_fma_f32 v226, |v166|, s88, 1.0
	v_fma_f32 v227, |v167|, s88, 1.0
	v_pk_mul_f32 v[224:225], v[160:161], v[160:161]
	v_pk_mul_f32 v[230:231], v[166:167], v[166:167]
	v_rcp_f32_e32 v220, v220
	v_rcp_f32_e32 v221, v221
	v_rcp_f32_e32 v226, v226
	v_rcp_f32_e32 v227, v227
	v_pk_mul_f32 v[224:225], v[224:225], s[72:73] op_sel_hi:[1,0]
	v_pk_mul_f32 v[230:231], v[230:231], s[72:73] op_sel_hi:[1,0]
	v_pk_fma_f32 v[222:223], v[220:221], s[90:91], v[232:233] op_sel_hi:[1,0,0]
	v_pk_fma_f32 v[228:229], v[226:227], s[90:91], v[232:233] op_sel_hi:[1,0,0]
	v_exp_f32_e32 v224, v224
	v_exp_f32_e32 v225, v225
	v_exp_f32_e32 v230, v230
	v_exp_f32_e32 v231, v231
	v_pk_fma_f32 v[222:223], v[220:221], v[222:223], s[94:95] op_sel_hi:[1,1,0]
	v_pk_fma_f32 v[228:229], v[226:227], v[228:229], s[94:95] op_sel_hi:[1,1,0]
	v_pk_fma_f32 v[222:223], v[220:221], v[222:223], s[96:97] op_sel_hi:[1,1,0]
	v_pk_fma_f32 v[228:229], v[226:227], v[228:229], s[96:97] op_sel_hi:[1,1,0]
	v_pk_fma_f32 v[222:223], v[220:221], v[222:223], s[98:99] op_sel_hi:[1,1,0]
	v_pk_fma_f32 v[228:229], v[226:227], v[228:229], s[98:99] op_sel_hi:[1,1,0]
	v_pk_mul_f32 v[222:223], v[220:221], v[222:223]
	v_pk_mul_f32 v[228:229], v[226:227], v[228:229]
	v_pk_mul_f32 v[222:223], v[224:225], v[222:223]
	v_pk_mul_f32 v[228:229], v[230:231], v[228:229]
	v_max_f32_e32 v220, 0, v160
	v_max_f32_e32 v221, 0, v161
	v_max_f32_e32 v226, 0, v166
	v_max_f32_e32 v227, 0, v167
	v_fma_f32 v160, -|v160|, v222, v220
	v_fma_f32 v161, -|v161|, v223, v221
	v_fma_f32 v166, -|v166|, v228, v226
	v_fma_f32 v167, -|v167|, v229, v227
.LBB0_136:
	s_nop 0
	v_cvt_pk_bf16_f32 v174, v164, v165
	v_cvt_pk_bf16_f32 v175, v162, v163
	v_cvt_pk_bf16_f32 v176, v160, v161
	v_cvt_pk_bf16_f32 v177, v166, v167
	v_pk_mul_f32 v[162:163], v[100:101], v[158:159] op_sel_hi:[1,0]
	v_pk_mul_f32 v[164:165], v[98:99], v[158:159] op_sel_hi:[1,0]
	v_pk_mul_f32 v[166:167], v[104:105], v[158:159] op_sel_hi:[1,0]
	s_and_b64 vcc, exec, s[6:7]
	v_pk_mul_f32 v[168:169], v[102:103], v[158:159] op_sel_hi:[1,0]
	global_store_dwordx4 v[156:157], v[174:177], off offset:64
	s_cbranch_vccnz .LBB0_138
	v_mov_b32_e32 v232, s68
	v_fma_f32 v220, |v164|, s88, 1.0
	v_fma_f32 v221, |v165|, s88, 1.0
	v_fma_f32 v226, |v162|, s88, 1.0
	v_fma_f32 v227, |v163|, s88, 1.0
	v_pk_mul_f32 v[224:225], v[164:165], v[164:165]
	v_pk_mul_f32 v[230:231], v[162:163], v[162:163]
	v_rcp_f32_e32 v220, v220
	v_rcp_f32_e32 v221, v221
	v_rcp_f32_e32 v226, v226
	v_rcp_f32_e32 v227, v227
	v_pk_mul_f32 v[224:225], v[224:225], s[72:73] op_sel_hi:[1,0]
	v_pk_mul_f32 v[230:231], v[230:231], s[72:73] op_sel_hi:[1,0]
	v_pk_fma_f32 v[222:223], v[220:221], s[90:91], v[232:233] op_sel_hi:[1,0,0]
	v_pk_fma_f32 v[228:229], v[226:227], s[90:91], v[232:233] op_sel_hi:[1,0,0]
	v_exp_f32_e32 v224, v224
	v_exp_f32_e32 v225, v225
	v_exp_f32_e32 v230, v230
	v_exp_f32_e32 v231, v231
	v_pk_fma_f32 v[222:223], v[220:221], v[222:223], s[94:95] op_sel_hi:[1,1,0]
	v_pk_fma_f32 v[228:229], v[226:227], v[228:229], s[94:95] op_sel_hi:[1,1,0]
	v_pk_fma_f32 v[222:223], v[220:221], v[222:223], s[96:97] op_sel_hi:[1,1,0]
	v_pk_fma_f32 v[228:229], v[226:227], v[228:229], s[96:97] op_sel_hi:[1,1,0]
	v_pk_fma_f32 v[222:223], v[220:221], v[222:223], s[98:99] op_sel_hi:[1,1,0]
	v_pk_fma_f32 v[228:229], v[226:227], v[228:229], s[98:99] op_sel_hi:[1,1,0]
	v_pk_mul_f32 v[222:223], v[220:221], v[222:223]
	v_pk_mul_f32 v[228:229], v[226:227], v[228:229]
	v_pk_mul_f32 v[222:223], v[224:225], v[222:223]
	v_pk_mul_f32 v[228:229], v[230:231], v[228:229]
	v_max_f32_e32 v220, 0, v164
	v_max_f32_e32 v221, 0, v165
	v_max_f32_e32 v226, 0, v162
	v_max_f32_e32 v227, 0, v163
	v_fma_f32 v164, -|v164|, v222, v220
	v_fma_f32 v165, -|v165|, v223, v221
	v_fma_f32 v162, -|v162|, v228, v226
	v_fma_f32 v163, -|v163|, v229, v227
	v_fma_f32 v220, |v168|, s88, 1.0
	v_fma_f32 v221, |v169|, s88, 1.0
	v_fma_f32 v226, |v166|, s88, 1.0
	v_fma_f32 v227, |v167|, s88, 1.0
; __device__ __forceinline__ unsigned pk_bf16(float lo, float hi) { f32x2 v = {lo, hi}; bf16x2_t b = __builtin_convertvector(v, bf16x2_t); return __builtin_bit_cast(unsigned, b); }
; __device__ __forceinline__ f32x4 gelu4(f32x4 v) { f32x2 a = gelu_pk((f32x2){v[0], v[1]}), b = gelu_pk((f32x2){v[2], v[3]}); return (f32x4){a.x, a.y, b.x, b.y}; }
; __device__ __forceinline__ f32x2 gelu_pk(f32x2 v) {
;     const f32x2 av = __builtin_elementwise_abs(v), d = av * 0.2316418882f + 1.0f;
;     f32x2 t; t.x = __builtin_amdgcn_rcpf(d.x); t.y = __builtin_amdgcn_rcpf(d.y);
;     f32x2 q = t * 0.5307027145f + (-0.7265760135f); q = q * t + 0.7107068705f; q = q * t + (-0.142248368f); q = q * t + 0.127414796f; q = q * t;
;     const f32x2 s = (v * v) * (-0.72134752044f);
;     f32x2 e; e.x = __builtin_amdgcn_exp2f(s.x); e.y = __builtin_amdgcn_exp2f(s.y);
;     const f32x2 m = v * (q * e), r = v - m;
;     f32x2 o; o.x = v.x < 0.f ? m.x : r.x; o.y = v.y < 0.f ? m.y : r.y; return o;
;     __device__ __forceinline__ void operator()(const f32x4 (&acc)[2][2][4][2], const Unit& u, int wr, int wc, int fr, int fq, float rp0, float rp1, const f32x4& raw0, const f32x4& raw1, float& rn0, float& rn1) const {
;     ...
;                         f32x4 v0 = acc[ai][bj][m][0] * r, v1 = acc[ai][bj][m][1] * r;
;                         if (gel) { v0 = gelu4(v0); v1 = gelu4(v1); }
;                         u32x4 w; w.x = pk_bf16(v0[0], v0[1]); w.y = pk_bf16(v0[2], v0[3]); w.z = pk_bf16(v1[0], v1[1]); w.w = pk_bf16(v1[2], v1[3]);
;                         *(u32x4*)(base + (size_t)roff * ld + bj * 32) = w;
	v_pk_mul_f32 v[224:225], v[168:169], v[168:169]
	v_pk_mul_f32 v[230:231], v[166:167], v[166:167]
	v_rcp_f32_e32 v220, v220
	v_rcp_f32_e32 v221, v221
	v_rcp_f32_e32 v226, v226
	v_rcp_f32_e32 v227, v227
	v_pk_mul_f32 v[224:225], v[224:225], s[72:73] op_sel_hi:[1,0]
	v_pk_mul_f32 v[230:231], v[230:231], s[72:73] op_sel_hi:[1,0]
	v_pk_fma_f32 v[222:223], v[220:221], s[90:91], v[232:233] op_sel_hi:[1,0,0]
	v_pk_fma_f32 v[228:229], v[226:227], s[90:91], v[232:233] op_sel_hi:[1,0,0]
	v_exp_f32_e32 v224, v224
	v_exp_f32_e32 v225, v225
	v_exp_f32_e32 v230, v230
	v_exp_f32_e32 v231, v231
	v_pk_fma_f32 v[222:223], v[220:221], v[222:223], s[94:95] op_sel_hi:[1,1,0]
	v_pk_fma_f32 v[228:229], v[226:227], v[228:229], s[94:95] op_sel_hi:[1,1,0]
	v_pk_fma_f32 v[222:223], v[220:221], v[222:223], s[96:97] op_sel_hi:[1,1,0]
	v_pk_fma_f32 v[228:229], v[226:227], v[228:229], s[96:97] op_sel_hi:[1,1,0]
	v_pk_fma_f32 v[222:223], v[220:221], v[222:223], s[98:99] op_sel_hi:[1,1,0]
	v_pk_fma_f32 v[228:229], v[226:227], v[228:229], s[98:99] op_sel_hi:[1,1,0]
	v_pk_mul_f32 v[222:223], v[220:221], v[222:223]
	v_pk_mul_f32 v[228:229], v[226:227], v[228:229]
	v_pk_mul_f32 v[222:223], v[224:225], v[222:223]
	v_pk_mul_f32 v[228:229], v[230:231], v[228:229]
	v_max_f32_e32 v220, 0, v168
	v_max_f32_e32 v221, 0, v169
	v_max_f32_e32 v226, 0, v166
	v_max_f32_e32 v227, 0, v167
	v_fma_f32 v168, -|v168|, v222, v220
	v_fma_f32 v169, -|v169|, v223, v221
	v_fma_f32 v166, -|v166|, v228, v226
	v_fma_f32 v167, -|v167|, v229, v227
.LBB0_138:
	v_mov_b32_e32 v159, v158
	s_lshl_b32 s76, s10, 5
	v_cvt_pk_bf16_f32 v177, v166, v167
	v_mov_b32_e32 v166, v158
	v_mov_b32_e32 v167, v158
	v_lshl_add_u64 v[160:161], v[156:157], 0, s[76:77]
	v_cvt_pk_bf16_f32 v174, v164, v165
	v_cvt_pk_bf16_f32 v175, v162, v163
	v_cvt_pk_bf16_f32 v176, v168, v169
	v_pk_mul_f32 v[162:163], v[108:109], v[166:167]
	v_pk_mul_f32 v[164:165], v[106:107], v[158:159]
	v_pk_mul_f32 v[166:167], v[112:113], v[166:167]
	s_and_b64 vcc, exec, s[6:7]
	v_pk_mul_f32 v[158:159], v[110:111], v[158:159]
	global_store_dwordx4 v[160:161], v[174:177], off
	s_cbranch_vccnz .LBB0_140
	v_mov_b32_e32 v232, s68
	v_fma_f32 v220, |v164|, s88, 1.0
	v_fma_f32 v221, |v165|, s88, 1.0
	v_fma_f32 v226, |v162|, s88, 1.0
	v_fma_f32 v227, |v163|, s88, 1.0
	v_pk_mul_f32 v[224:225], v[164:165], v[164:165]
	v_pk_mul_f32 v[230:231], v[162:163], v[162:163]
	v_rcp_f32_e32 v220, v220
	v_rcp_f32_e32 v221, v221
	v_rcp_f32_e32 v226, v226
	v_rcp_f32_e32 v227, v227
	v_pk_mul_f32 v[224:225], v[224:225], s[72:73] op_sel_hi:[1,0]
	v_pk_mul_f32 v[230:231], v[230:231], s[72:73] op_sel_hi:[1,0]
	v_pk_fma_f32 v[222:223], v[220:221], s[90:91], v[232:233] op_sel_hi:[1,0,0]
	v_pk_fma_f32 v[228:229], v[226:227], s[90:91], v[232:233] op_sel_hi:[1,0,0]
	v_exp_f32_e32 v224, v224
	v_exp_f32_e32 v225, v225
	v_exp_f32_e32 v230, v230
	v_exp_f32_e32 v231, v231
	v_pk_fma_f32 v[222:223], v[220:221], v[222:223], s[94:95] op_sel_hi:[1,1,0]
	v_pk_fma_f32 v[228:229], v[226:227], v[228:229], s[94:95] op_sel_hi:[1,1,0]
	v_pk_fma_f32 v[222:223], v[220:221], v[222:223], s[96:97] op_sel_hi:[1,1,0]
	v_pk_fma_f32 v[228:229], v[226:227], v[228:229], s[96:97] op_sel_hi:[1,1,0]
	v_pk_fma_f32 v[222:223], v[220:221], v[222:223], s[98:99] op_sel_hi:[1,1,0]
	v_pk_fma_f32 v[228:229], v[226:227], v[228:229], s[98:99] op_sel_hi:[1,1,0]
	v_pk_mul_f32 v[222:223], v[220:221], v[222:223]
	v_pk_mul_f32 v[228:229], v[226:227], v[228:229]
	v_pk_mul_f32 v[222:223], v[224:225], v[222:223]
	v_pk_mul_f32 v[228:229], v[230:231], v[228:229]
	v_max_f32_e32 v220, 0, v164
	v_max_f32_e32 v221, 0, v165
	v_max_f32_e32 v226, 0, v162
	v_max_f32_e32 v227, 0, v163
	v_fma_f32 v164, -|v164|, v222, v220
	v_fma_f32 v165, -|v165|, v223, v221
	v_fma_f32 v162, -|v162|, v228, v226
	v_fma_f32 v163, -|v163|, v229, v227
	v_fma_f32 v220, |v158|, s88, 1.0
	v_fma_f32 v221, |v159|, s88, 1.0
	v_fma_f32 v226, |v166|, s88, 1.0
	v_fma_f32 v227, |v167|, s88, 1.0
	v_pk_mul_f32 v[224:225], v[158:159], v[158:159]
	v_pk_mul_f32 v[230:231], v[166:167], v[166:167]
	v_rcp_f32_e32 v220, v220
	v_rcp_f32_e32 v221, v221
	v_rcp_f32_e32 v226, v226
	v_rcp_f32_e32 v227, v227
	v_pk_mul_f32 v[224:225], v[224:225], s[72:73] op_sel_hi:[1,0]
	v_pk_mul_f32 v[230:231], v[230:231], s[72:73] op_sel_hi:[1,0]
	v_pk_fma_f32 v[222:223], v[220:221], s[90:91], v[232:233] op_sel_hi:[1,0,0]
	v_pk_fma_f32 v[228:229], v[226:227], s[90:91], v[232:233] op_sel_hi:[1,0,0]
	v_exp_f32_e32 v224, v224
	v_exp_f32_e32 v225, v225
	v_exp_f32_e32 v230, v230
	v_exp_f32_e32 v231, v231
	v_pk_fma_f32 v[222:223], v[220:221], v[222:223], s[94:95] op_sel_hi:[1,1,0]
	v_pk_fma_f32 v[228:229], v[226:227], v[228:229], s[94:95] op_sel_hi:[1,1,0]
	v_pk_fma_f32 v[222:223], v[220:221], v[222:223], s[96:97] op_sel_hi:[1,1,0]
	v_pk_fma_f32 v[228:229], v[226:227], v[228:229], s[96:97] op_sel_hi:[1,1,0]
	v_pk_fma_f32 v[222:223], v[220:221], v[222:223], s[98:99] op_sel_hi:[1,1,0]
	v_pk_fma_f32 v[228:229], v[226:227], v[228:229], s[98:99] op_sel_hi:[1,1,0]
	v_pk_mul_f32 v[222:223], v[220:221], v[222:223]
	v_pk_mul_f32 v[228:229], v[226:227], v[228:229]
	v_pk_mul_f32 v[222:223], v[224:225], v[222:223]
	v_pk_mul_f32 v[228:229], v[230:231], v[228:229]
	v_max_f32_e32 v220, 0, v158
	v_max_f32_e32 v221, 0, v159
	v_max_f32_e32 v226, 0, v166
	v_max_f32_e32 v227, 0, v167
	v_fma_f32 v158, -|v158|, v222, v220
	v_fma_f32 v159, -|v159|, v223, v221
	v_fma_f32 v166, -|v166|, v228, v226
	v_fma_f32 v167, -|v167|, v229, v227
; __device__ __forceinline__ unsigned pk_bf16(float lo, float hi) { f32x2 v = {lo, hi}; bf16x2_t b = __builtin_convertvector(v, bf16x2_t); return __builtin_bit_cast(unsigned, b); }
; __device__ __forceinline__ f32x4 gelu4(f32x4 v) { f32x2 a = gelu_pk((f32x2){v[0], v[1]}), b = gelu_pk((f32x2){v[2], v[3]}); return (f32x4){a.x, a.y, b.x, b.y}; }
; __device__ __forceinline__ f32x2 gelu_pk(f32x2 v) {
;     const f32x2 av = __builtin_elementwise_abs(v), d = av * 0.2316418882f + 1.0f;
;     f32x2 t; t.x = __builtin_amdgcn_rcpf(d.x); t.y = __builtin_amdgcn_rcpf(d.y);
;     f32x2 q = t * 0.5307027145f + (-0.7265760135f); q = q * t + 0.7107068705f; q = q * t + (-0.142248368f); q = q * t + 0.127414796f; q = q * t;
;     const f32x2 s = (v * v) * (-0.72134752044f);
;     f32x2 e; e.x = __builtin_amdgcn_exp2f(s.x); e.y = __builtin_amdgcn_exp2f(s.y);
;     const f32x2 m = v * (q * e), r = v - m;
;     f32x2 o; o.x = v.x < 0.f ? m.x : r.x; o.y = v.y < 0.f ? m.y : r.y; return o;
;     __device__ __forceinline__ void operator()(const f32x4 (&acc)[2][2][4][2], const Unit& u, int wr, int wc, int fr, int fq, float rp0, float rp1, const f32x4& raw0, const f32x4& raw1, float& rn0, float& rn1) const {
;     ...
;                         f32x4 v0 = acc[ai][bj][m][0] * r, v1 = acc[ai][bj][m][1] * r;
;                         if (gel) { v0 = gelu4(v0); v1 = gelu4(v1); }
;                         u32x4 w; w.x = pk_bf16(v0[0], v0[1]); w.y = pk_bf16(v0[2], v0[3]); w.z = pk_bf16(v1[0], v1[1]); w.w = pk_bf16(v1[2], v1[3]);
;                         *(u32x4*)(base + (size_t)roff * ld + bj * 32) = w;
.LBB0_140:
	s_nop 0
	v_cvt_pk_bf16_f32 v174, v164, v165
	v_cvt_pk_bf16_f32 v175, v162, v163
	v_cvt_pk_bf16_f32 v176, v158, v159
	v_cvt_pk_bf16_f32 v177, v166, v167
	v_pk_mul_f32 v[162:163], v[76:77], v[140:141] op_sel_hi:[1,0]
	v_pk_mul_f32 v[164:165], v[74:75], v[140:141] op_sel_hi:[1,0]
	v_pk_mul_f32 v[166:167], v[80:81], v[140:141] op_sel_hi:[1,0]
	s_and_b64 vcc, exec, s[6:7]
	v_pk_mul_f32 v[168:169], v[78:79], v[140:141] op_sel_hi:[1,0]
	global_store_dwordx4 v[160:161], v[174:177], off offset:64
	s_cbranch_vccnz .LBB0_142
	v_mov_b32_e32 v232, s68
	v_fma_f32 v220, |v164|, s88, 1.0
	v_fma_f32 v221, |v165|, s88, 1.0
	v_fma_f32 v226, |v162|, s88, 1.0
	v_fma_f32 v227, |v163|, s88, 1.0
	v_pk_mul_f32 v[224:225], v[164:165], v[164:165]
	v_pk_mul_f32 v[230:231], v[162:163], v[162:163]
	v_rcp_f32_e32 v220, v220
	v_rcp_f32_e32 v221, v221
	v_rcp_f32_e32 v226, v226
	v_rcp_f32_e32 v227, v227
	v_pk_mul_f32 v[224:225], v[224:225], s[72:73] op_sel_hi:[1,0]
	v_pk_mul_f32 v[230:231], v[230:231], s[72:73] op_sel_hi:[1,0]
	v_pk_fma_f32 v[222:223], v[220:221], s[90:91], v[232:233] op_sel_hi:[1,0,0]
	v_pk_fma_f32 v[228:229], v[226:227], s[90:91], v[232:233] op_sel_hi:[1,0,0]
	v_exp_f32_e32 v224, v224
	v_exp_f32_e32 v225, v225
	v_exp_f32_e32 v230, v230
	v_exp_f32_e32 v231, v231
	v_pk_fma_f32 v[222:223], v[220:221], v[222:223], s[94:95] op_sel_hi:[1,1,0]
	v_pk_fma_f32 v[228:229], v[226:227], v[228:229], s[94:95] op_sel_hi:[1,1,0]
	v_pk_fma_f32 v[222:223], v[220:221], v[222:223], s[96:97] op_sel_hi:[1,1,0]
	v_pk_fma_f32 v[228:229], v[226:227], v[228:229], s[96:97] op_sel_hi:[1,1,0]
	v_pk_fma_f32 v[222:223], v[220:221], v[222:223], s[98:99] op_sel_hi:[1,1,0]
	v_pk_fma_f32 v[228:229], v[226:227], v[228:229], s[98:99] op_sel_hi:[1,1,0]
	v_pk_mul_f32 v[222:223], v[220:221], v[222:223]
	v_pk_mul_f32 v[228:229], v[226:227], v[228:229]
	v_pk_mul_f32 v[222:223], v[224:225], v[222:223]
	v_pk_mul_f32 v[228:229], v[230:231], v[228:229]
	v_max_f32_e32 v220, 0, v164
	v_max_f32_e32 v221, 0, v165
	v_max_f32_e32 v226, 0, v162
	v_max_f32_e32 v227, 0, v163
	v_fma_f32 v164, -|v164|, v222, v220
	v_fma_f32 v165, -|v165|, v223, v221
	v_fma_f32 v162, -|v162|, v228, v226
	v_fma_f32 v163, -|v163|, v229, v227
	v_fma_f32 v220, |v168|, s88, 1.0
	v_fma_f32 v221, |v169|, s88, 1.0
	v_fma_f32 v226, |v166|, s88, 1.0
	v_fma_f32 v227, |v167|, s88, 1.0
	v_pk_mul_f32 v[224:225], v[168:169], v[168:169]
	v_pk_mul_f32 v[230:231], v[166:167], v[166:167]
	v_rcp_f32_e32 v220, v220
	v_rcp_f32_e32 v221, v221
	v_rcp_f32_e32 v226, v226
	v_rcp_f32_e32 v227, v227
	v_pk_mul_f32 v[224:225], v[224:225], s[72:73] op_sel_hi:[1,0]
	v_pk_mul_f32 v[230:231], v[230:231], s[72:73] op_sel_hi:[1,0]
	v_pk_fma_f32 v[222:223], v[220:221], s[90:91], v[232:233] op_sel_hi:[1,0,0]
	v_pk_fma_f32 v[228:229], v[226:227], s[90:91], v[232:233] op_sel_hi:[1,0,0]
	v_exp_f32_e32 v224, v224
	v_exp_f32_e32 v225, v225
	v_exp_f32_e32 v230, v230
	v_exp_f32_e32 v231, v231
	v_pk_fma_f32 v[222:223], v[220:221], v[222:223], s[94:95] op_sel_hi:[1,1,0]
	v_pk_fma_f32 v[228:229], v[226:227], v[228:229], s[94:95] op_sel_hi:[1,1,0]
	v_pk_fma_f32 v[222:223], v[220:221], v[222:223], s[96:97] op_sel_hi:[1,1,0]
	v_pk_fma_f32 v[228:229], v[226:227], v[228:229], s[96:97] op_sel_hi:[1,1,0]
	v_pk_fma_f32 v[222:223], v[220:221], v[222:223], s[98:99] op_sel_hi:[1,1,0]
	v_pk_fma_f32 v[228:229], v[226:227], v[228:229], s[98:99] op_sel_hi:[1,1,0]
	v_pk_mul_f32 v[222:223], v[220:221], v[222:223]
	v_pk_mul_f32 v[228:229], v[226:227], v[228:229]
	v_pk_mul_f32 v[222:223], v[224:225], v[222:223]
	v_pk_mul_f32 v[228:229], v[230:231], v[228:229]
	v_max_f32_e32 v220, 0, v168
	v_max_f32_e32 v221, 0, v169
	v_max_f32_e32 v226, 0, v166
	v_max_f32_e32 v227, 0, v167
	v_fma_f32 v168, -|v168|, v222, v220
	v_fma_f32 v169, -|v169|, v223, v221
	v_fma_f32 v166, -|v166|, v228, v226
	v_fma_f32 v167, -|v167|, v229, v227
.LBB0_142:
	v_mov_b32_e32 v141, v140
	v_lshl_add_u64 v[158:159], v[160:161], 0, s[76:77]
	v_cvt_pk_bf16_f32 v160, v164, v165
	v_cvt_pk_bf16_f32 v161, v162, v163
	v_cvt_pk_bf16_f32 v162, v168, v169
	v_cvt_pk_bf16_f32 v163, v166, v167
	v_mov_b32_e32 v164, v140
	v_mov_b32_e32 v165, v140
	global_store_dwordx4 v[158:159], v[160:163], off
	s_and_b64 vcc, exec, s[6:7]
	s_nop 0
	v_pk_mul_f32 v[160:161], v[92:93], v[164:165]
	v_pk_mul_f32 v[162:163], v[90:91], v[140:141]
	v_pk_mul_f32 v[164:165], v[96:97], v[164:165]
	v_pk_mul_f32 v[140:141], v[94:95], v[140:141]
	s_cbranch_vccnz .LBB0_144
; __device__ __forceinline__ unsigned pk_bf16(float lo, float hi) { f32x2 v = {lo, hi}; bf16x2_t b = __builtin_convertvector(v, bf16x2_t); return __builtin_bit_cast(unsigned, b); }
; __device__ __forceinline__ f32x4 gelu4(f32x4 v) { f32x2 a = gelu_pk((f32x2){v[0], v[1]}), b = gelu_pk((f32x2){v[2], v[3]}); return (f32x4){a.x, a.y, b.x, b.y}; }
; __device__ __forceinline__ f32x2 gelu_pk(f32x2 v) {
;     const f32x2 av = __builtin_elementwise_abs(v), d = av * 0.2316418882f + 1.0f;
;     f32x2 t; t.x = __builtin_amdgcn_rcpf(d.x); t.y = __builtin_amdgcn_rcpf(d.y);
;     f32x2 q = t * 0.5307027145f + (-0.7265760135f); q = q * t + 0.7107068705f; q = q * t + (-0.142248368f); q = q * t + 0.127414796f; q = q * t;
;     const f32x2 s = (v * v) * (-0.72134752044f);
;     f32x2 e; e.x = __builtin_amdgcn_exp2f(s.x); e.y = __builtin_amdgcn_exp2f(s.y);
;     const f32x2 m = v * (q * e), r = v - m;
;     f32x2 o; o.x = v.x < 0.f ? m.x : r.x; o.y = v.y < 0.f ? m.y : r.y; return o;
;     __device__ __forceinline__ void operator()(const f32x4 (&acc)[2][2][4][2], const Unit& u, int wr, int wc, int fr, int fq, float rp0, float rp1, const f32x4& raw0, const f32x4& raw1, float& rn0, float& rn1) const {
;     ...
;                         f32x4 v0 = acc[ai][bj][m][0] * r, v1 = acc[ai][bj][m][1] * r;
;                         if (gel) { v0 = gelu4(v0); v1 = gelu4(v1); }
;                         u32x4 w; w.x = pk_bf16(v0[0], v0[1]); w.y = pk_bf16(v0[2], v0[3]); w.z = pk_bf16(v1[0], v1[1]); w.w = pk_bf16(v1[2], v1[3]);
;                         *(u32x4*)(base + (size_t)roff * ld + bj * 32) = w;
	v_mov_b32_e32 v232, s68
	v_fma_f32 v220, |v162|, s88, 1.0
	v_fma_f32 v221, |v163|, s88, 1.0
	v_fma_f32 v226, |v160|, s88, 1.0
	v_fma_f32 v227, |v161|, s88, 1.0
	v_pk_mul_f32 v[224:225], v[162:163], v[162:163]
	v_pk_mul_f32 v[230:231], v[160:161], v[160:161]
	v_rcp_f32_e32 v220, v220
	v_rcp_f32_e32 v221, v221
	v_rcp_f32_e32 v226, v226
	v_rcp_f32_e32 v227, v227
	v_pk_mul_f32 v[224:225], v[224:225], s[72:73] op_sel_hi:[1,0]
	v_pk_mul_f32 v[230:231], v[230:231], s[72:73] op_sel_hi:[1,0]
	v_pk_fma_f32 v[222:223], v[220:221], s[90:91], v[232:233] op_sel_hi:[1,0,0]
	v_pk_fma_f32 v[228:229], v[226:227], s[90:91], v[232:233] op_sel_hi:[1,0,0]
	v_exp_f32_e32 v224, v224
	v_exp_f32_e32 v225, v225
	v_exp_f32_e32 v230, v230
	v_exp_f32_e32 v231, v231
	v_pk_fma_f32 v[222:223], v[220:221], v[222:223], s[94:95] op_sel_hi:[1,1,0]
	v_pk_fma_f32 v[228:229], v[226:227], v[228:229], s[94:95] op_sel_hi:[1,1,0]
	v_pk_fma_f32 v[222:223], v[220:221], v[222:223], s[96:97] op_sel_hi:[1,1,0]
	v_pk_fma_f32 v[228:229], v[226:227], v[228:229], s[96:97] op_sel_hi:[1,1,0]
	v_pk_fma_f32 v[222:223], v[220:221], v[222:223], s[98:99] op_sel_hi:[1,1,0]
	v_pk_fma_f32 v[228:229], v[226:227], v[228:229], s[98:99] op_sel_hi:[1,1,0]
	v_pk_mul_f32 v[222:223], v[220:221], v[222:223]
	v_pk_mul_f32 v[228:229], v[226:227], v[228:229]
	v_pk_mul_f32 v[222:223], v[224:225], v[222:223]
	v_pk_mul_f32 v[228:229], v[230:231], v[228:229]
	v_max_f32_e32 v220, 0, v162
	v_max_f32_e32 v221, 0, v163
	v_max_f32_e32 v226, 0, v160
	v_max_f32_e32 v227, 0, v161
	v_fma_f32 v162, -|v162|, v222, v220
	v_fma_f32 v163, -|v163|, v223, v221
	v_fma_f32 v160, -|v160|, v228, v226
	v_fma_f32 v161, -|v161|, v229, v227
	v_fma_f32 v220, |v140|, s88, 1.0
	v_fma_f32 v221, |v141|, s88, 1.0
	v_fma_f32 v226, |v164|, s88, 1.0
	v_fma_f32 v227, |v165|, s88, 1.0
	v_pk_mul_f32 v[224:225], v[140:141], v[140:141]
	v_pk_mul_f32 v[230:231], v[164:165], v[164:165]
	v_rcp_f32_e32 v220, v220
	v_rcp_f32_e32 v221, v221
	v_rcp_f32_e32 v226, v226
	v_rcp_f32_e32 v227, v227
	v_pk_mul_f32 v[224:225], v[224:225], s[72:73] op_sel_hi:[1,0]
	v_pk_mul_f32 v[230:231], v[230:231], s[72:73] op_sel_hi:[1,0]
	v_pk_fma_f32 v[222:223], v[220:221], s[90:91], v[232:233] op_sel_hi:[1,0,0]
	v_pk_fma_f32 v[228:229], v[226:227], s[90:91], v[232:233] op_sel_hi:[1,0,0]
	v_exp_f32_e32 v224, v224
	v_exp_f32_e32 v225, v225
	v_exp_f32_e32 v230, v230
	v_exp_f32_e32 v231, v231
	v_pk_fma_f32 v[222:223], v[220:221], v[222:223], s[94:95] op_sel_hi:[1,1,0]
	v_pk_fma_f32 v[228:229], v[226:227], v[228:229], s[94:95] op_sel_hi:[1,1,0]
	v_pk_fma_f32 v[222:223], v[220:221], v[222:223], s[96:97] op_sel_hi:[1,1,0]
	v_pk_fma_f32 v[228:229], v[226:227], v[228:229], s[96:97] op_sel_hi:[1,1,0]
	v_pk_fma_f32 v[222:223], v[220:221], v[222:223], s[98:99] op_sel_hi:[1,1,0]
	v_pk_fma_f32 v[228:229], v[226:227], v[228:229], s[98:99] op_sel_hi:[1,1,0]
	v_pk_mul_f32 v[222:223], v[220:221], v[222:223]
	v_pk_mul_f32 v[228:229], v[226:227], v[228:229]
	v_pk_mul_f32 v[222:223], v[224:225], v[222:223]
	v_pk_mul_f32 v[228:229], v[230:231], v[228:229]
	v_max_f32_e32 v220, 0, v140
	v_max_f32_e32 v221, 0, v141
	v_max_f32_e32 v226, 0, v164
	v_max_f32_e32 v227, 0, v165
	v_fma_f32 v140, -|v140|, v222, v220
	v_fma_f32 v141, -|v141|, v223, v221
	v_fma_f32 v164, -|v164|, v228, v226
	v_fma_f32 v165, -|v165|, v229, v227
.LBB0_144:
	v_cvt_pk_bf16_f32 v166, v162, v163
	v_cvt_pk_bf16_f32 v167, v160, v161
	v_cvt_pk_bf16_f32 v168, v140, v141
	v_cvt_pk_bf16_f32 v169, v164, v165
	global_store_dwordx4 v[158:159], v[166:169], off offset:64
	v_pk_mul_f32 v[140:141], v[68:69], v[138:139] op_sel_hi:[1,0]
	v_pk_mul_f32 v[162:163], v[66:67], v[138:139] op_sel_hi:[1,0]
	v_pk_mul_f32 v[164:165], v[72:73], v[138:139] op_sel_hi:[1,0]
	s_and_b64 vcc, exec, s[6:7]
	v_pk_mul_f32 v[166:167], v[70:71], v[138:139] op_sel_hi:[1,0]
	s_cbranch_vccnz .LBB0_146
	v_mov_b32_e32 v232, s68
	v_fma_f32 v220, |v162|, s88, 1.0
	v_fma_f32 v221, |v163|, s88, 1.0
	v_fma_f32 v226, |v140|, s88, 1.0
	v_fma_f32 v227, |v141|, s88, 1.0
	v_pk_mul_f32 v[224:225], v[162:163], v[162:163]
	v_pk_mul_f32 v[230:231], v[140:141], v[140:141]
	v_rcp_f32_e32 v220, v220
	v_rcp_f32_e32 v221, v221
	v_rcp_f32_e32 v226, v226
	v_rcp_f32_e32 v227, v227
	v_pk_mul_f32 v[224:225], v[224:225], s[72:73] op_sel_hi:[1,0]
	v_pk_mul_f32 v[230:231], v[230:231], s[72:73] op_sel_hi:[1,0]
	v_pk_fma_f32 v[222:223], v[220:221], s[90:91], v[232:233] op_sel_hi:[1,0,0]
	v_pk_fma_f32 v[228:229], v[226:227], s[90:91], v[232:233] op_sel_hi:[1,0,0]
	v_exp_f32_e32 v224, v224
	v_exp_f32_e32 v225, v225
	v_exp_f32_e32 v230, v230
	v_exp_f32_e32 v231, v231
	v_pk_fma_f32 v[222:223], v[220:221], v[222:223], s[94:95] op_sel_hi:[1,1,0]
	v_pk_fma_f32 v[228:229], v[226:227], v[228:229], s[94:95] op_sel_hi:[1,1,0]
	v_pk_fma_f32 v[222:223], v[220:221], v[222:223], s[96:97] op_sel_hi:[1,1,0]
	v_pk_fma_f32 v[228:229], v[226:227], v[228:229], s[96:97] op_sel_hi:[1,1,0]
	v_pk_fma_f32 v[222:223], v[220:221], v[222:223], s[98:99] op_sel_hi:[1,1,0]
	v_pk_fma_f32 v[228:229], v[226:227], v[228:229], s[98:99] op_sel_hi:[1,1,0]
	v_pk_mul_f32 v[222:223], v[220:221], v[222:223]
	v_pk_mul_f32 v[228:229], v[226:227], v[228:229]
	v_pk_mul_f32 v[222:223], v[224:225], v[222:223]
	v_pk_mul_f32 v[228:229], v[230:231], v[228:229]
	v_max_f32_e32 v220, 0, v162
	v_max_f32_e32 v221, 0, v163
	v_max_f32_e32 v226, 0, v140
	v_max_f32_e32 v227, 0, v141
	v_fma_f32 v162, -|v162|, v222, v220
	v_fma_f32 v163, -|v163|, v223, v221
	v_fma_f32 v140, -|v140|, v228, v226
	v_fma_f32 v141, -|v141|, v229, v227
	v_fma_f32 v220, |v166|, s88, 1.0
	v_fma_f32 v221, |v167|, s88, 1.0
	v_fma_f32 v226, |v164|, s88, 1.0
	v_fma_f32 v227, |v165|, s88, 1.0
; __device__ __forceinline__ unsigned pk_bf16(float lo, float hi) { f32x2 v = {lo, hi}; bf16x2_t b = __builtin_convertvector(v, bf16x2_t); return __builtin_bit_cast(unsigned, b); }
; __device__ __forceinline__ f32x4 gelu4(f32x4 v) { f32x2 a = gelu_pk((f32x2){v[0], v[1]}), b = gelu_pk((f32x2){v[2], v[3]}); return (f32x4){a.x, a.y, b.x, b.y}; }
; __device__ __forceinline__ f32x2 gelu_pk(f32x2 v) {
;     const f32x2 av = __builtin_elementwise_abs(v), d = av * 0.2316418882f + 1.0f;
;     f32x2 t; t.x = __builtin_amdgcn_rcpf(d.x); t.y = __builtin_amdgcn_rcpf(d.y);
;     f32x2 q = t * 0.5307027145f + (-0.7265760135f); q = q * t + 0.7107068705f; q = q * t + (-0.142248368f); q = q * t + 0.127414796f; q = q * t;
;     const f32x2 s = (v * v) * (-0.72134752044f);
;     f32x2 e; e.x = __builtin_amdgcn_exp2f(s.x); e.y = __builtin_amdgcn_exp2f(s.y);
;     const f32x2 m = v * (q * e), r = v - m;
;     f32x2 o; o.x = v.x < 0.f ? m.x : r.x; o.y = v.y < 0.f ? m.y : r.y; return o;
;     __device__ __forceinline__ void operator()(const f32x4 (&acc)[2][2][4][2], const Unit& u, int wr, int wc, int fr, int fq, float rp0, float rp1, const f32x4& raw0, const f32x4& raw1, float& rn0, float& rn1) const {
;     ...
;                         f32x4 v0 = acc[ai][bj][m][0] * r, v1 = acc[ai][bj][m][1] * r;
;                         if (gel) { v0 = gelu4(v0); v1 = gelu4(v1); }
;                         u32x4 w; w.x = pk_bf16(v0[0], v0[1]); w.y = pk_bf16(v0[2], v0[3]); w.z = pk_bf16(v1[0], v1[1]); w.w = pk_bf16(v1[2], v1[3]);
;                         *(u32x4*)(base + (size_t)roff * ld + bj * 32) = w;
	v_pk_mul_f32 v[224:225], v[166:167], v[166:167]
	v_pk_mul_f32 v[230:231], v[164:165], v[164:165]
	v_rcp_f32_e32 v220, v220
	v_rcp_f32_e32 v221, v221
	v_rcp_f32_e32 v226, v226
	v_rcp_f32_e32 v227, v227
	v_pk_mul_f32 v[224:225], v[224:225], s[72:73] op_sel_hi:[1,0]
	v_pk_mul_f32 v[230:231], v[230:231], s[72:73] op_sel_hi:[1,0]
	v_pk_fma_f32 v[222:223], v[220:221], s[90:91], v[232:233] op_sel_hi:[1,0,0]
	v_pk_fma_f32 v[228:229], v[226:227], s[90:91], v[232:233] op_sel_hi:[1,0,0]
	v_exp_f32_e32 v224, v224
	v_exp_f32_e32 v225, v225
	v_exp_f32_e32 v230, v230
	v_exp_f32_e32 v231, v231
	v_pk_fma_f32 v[222:223], v[220:221], v[222:223], s[94:95] op_sel_hi:[1,1,0]
	v_pk_fma_f32 v[228:229], v[226:227], v[228:229], s[94:95] op_sel_hi:[1,1,0]
	v_pk_fma_f32 v[222:223], v[220:221], v[222:223], s[96:97] op_sel_hi:[1,1,0]
	v_pk_fma_f32 v[228:229], v[226:227], v[228:229], s[96:97] op_sel_hi:[1,1,0]
	v_pk_fma_f32 v[222:223], v[220:221], v[222:223], s[98:99] op_sel_hi:[1,1,0]
	v_pk_fma_f32 v[228:229], v[226:227], v[228:229], s[98:99] op_sel_hi:[1,1,0]
	v_pk_mul_f32 v[222:223], v[220:221], v[222:223]
	v_pk_mul_f32 v[228:229], v[226:227], v[228:229]
	v_pk_mul_f32 v[222:223], v[224:225], v[222:223]
	v_pk_mul_f32 v[228:229], v[230:231], v[228:229]
	v_max_f32_e32 v220, 0, v166
	v_max_f32_e32 v221, 0, v167
	v_max_f32_e32 v226, 0, v164
	v_max_f32_e32 v227, 0, v165
	v_fma_f32 v166, -|v166|, v222, v220
	v_fma_f32 v167, -|v167|, v223, v221
	v_fma_f32 v164, -|v164|, v228, v226
	v_fma_f32 v165, -|v165|, v229, v227
.LBB0_146:
	v_mov_b32_e32 v139, v138
	v_cvt_pk_bf16_f32 v174, v162, v163
	v_mov_b32_e32 v162, v138
	v_mov_b32_e32 v163, v138
	v_lshl_add_u64 v[160:161], v[158:159], 0, s[76:77]
	v_cvt_pk_bf16_f32 v175, v140, v141
	v_cvt_pk_bf16_f32 v176, v166, v167
	v_cvt_pk_bf16_f32 v177, v164, v165
	v_pk_mul_f32 v[140:141], v[84:85], v[162:163]
	v_pk_mul_f32 v[158:159], v[82:83], v[138:139]
	v_pk_mul_f32 v[162:163], v[88:89], v[162:163]
	s_and_b64 vcc, exec, s[6:7]
	v_pk_mul_f32 v[138:139], v[86:87], v[138:139]
	global_store_dwordx4 v[160:161], v[174:177], off
	s_cbranch_vccnz .LBB0_148
	v_mov_b32_e32 v232, s68
	v_fma_f32 v220, |v158|, s88, 1.0
	v_fma_f32 v221, |v159|, s88, 1.0
	v_fma_f32 v226, |v140|, s88, 1.0
	v_fma_f32 v227, |v141|, s88, 1.0
	v_pk_mul_f32 v[224:225], v[158:159], v[158:159]
	v_pk_mul_f32 v[230:231], v[140:141], v[140:141]
	v_rcp_f32_e32 v220, v220
	v_rcp_f32_e32 v221, v221
	v_rcp_f32_e32 v226, v226
	v_rcp_f32_e32 v227, v227
	v_pk_mul_f32 v[224:225], v[224:225], s[72:73] op_sel_hi:[1,0]
	v_pk_mul_f32 v[230:231], v[230:231], s[72:73] op_sel_hi:[1,0]
	v_pk_fma_f32 v[222:223], v[220:221], s[90:91], v[232:233] op_sel_hi:[1,0,0]
	v_pk_fma_f32 v[228:229], v[226:227], s[90:91], v[232:233] op_sel_hi:[1,0,0]
	v_exp_f32_e32 v224, v224
	v_exp_f32_e32 v225, v225
	v_exp_f32_e32 v230, v230
	v_exp_f32_e32 v231, v231
	v_pk_fma_f32 v[222:223], v[220:221], v[222:223], s[94:95] op_sel_hi:[1,1,0]
	v_pk_fma_f32 v[228:229], v[226:227], v[228:229], s[94:95] op_sel_hi:[1,1,0]
	v_pk_fma_f32 v[222:223], v[220:221], v[222:223], s[96:97] op_sel_hi:[1,1,0]
	v_pk_fma_f32 v[228:229], v[226:227], v[228:229], s[96:97] op_sel_hi:[1,1,0]
	v_pk_fma_f32 v[222:223], v[220:221], v[222:223], s[98:99] op_sel_hi:[1,1,0]
	v_pk_fma_f32 v[228:229], v[226:227], v[228:229], s[98:99] op_sel_hi:[1,1,0]
	v_pk_mul_f32 v[222:223], v[220:221], v[222:223]
	v_pk_mul_f32 v[228:229], v[226:227], v[228:229]
	v_pk_mul_f32 v[222:223], v[224:225], v[222:223]
	v_pk_mul_f32 v[228:229], v[230:231], v[228:229]
	v_max_f32_e32 v220, 0, v158
	v_max_f32_e32 v221, 0, v159
	v_max_f32_e32 v226, 0, v140
	v_max_f32_e32 v227, 0, v141
	v_fma_f32 v158, -|v158|, v222, v220
	v_fma_f32 v159, -|v159|, v223, v221
	v_fma_f32 v140, -|v140|, v228, v226
	v_fma_f32 v141, -|v141|, v229, v227
	v_fma_f32 v220, |v138|, s88, 1.0
	v_fma_f32 v221, |v139|, s88, 1.0
	v_fma_f32 v226, |v162|, s88, 1.0
	v_fma_f32 v227, |v163|, s88, 1.0
	v_pk_mul_f32 v[224:225], v[138:139], v[138:139]
	v_pk_mul_f32 v[230:231], v[162:163], v[162:163]
	v_rcp_f32_e32 v220, v220
	v_rcp_f32_e32 v221, v221
	v_rcp_f32_e32 v226, v226
	v_rcp_f32_e32 v227, v227
	v_pk_mul_f32 v[224:225], v[224:225], s[72:73] op_sel_hi:[1,0]
	v_pk_mul_f32 v[230:231], v[230:231], s[72:73] op_sel_hi:[1,0]
	v_pk_fma_f32 v[222:223], v[220:221], s[90:91], v[232:233] op_sel_hi:[1,0,0]
	v_pk_fma_f32 v[228:229], v[226:227], s[90:91], v[232:233] op_sel_hi:[1,0,0]
	v_exp_f32_e32 v224, v224
	v_exp_f32_e32 v225, v225
	v_exp_f32_e32 v230, v230
	v_exp_f32_e32 v231, v231
	v_pk_fma_f32 v[222:223], v[220:221], v[222:223], s[94:95] op_sel_hi:[1,1,0]
	v_pk_fma_f32 v[228:229], v[226:227], v[228:229], s[94:95] op_sel_hi:[1,1,0]
	v_pk_fma_f32 v[222:223], v[220:221], v[222:223], s[96:97] op_sel_hi:[1,1,0]
	v_pk_fma_f32 v[228:229], v[226:227], v[228:229], s[96:97] op_sel_hi:[1,1,0]
	v_pk_fma_f32 v[222:223], v[220:221], v[222:223], s[98:99] op_sel_hi:[1,1,0]
	v_pk_fma_f32 v[228:229], v[226:227], v[228:229], s[98:99] op_sel_hi:[1,1,0]
	v_pk_mul_f32 v[222:223], v[220:221], v[222:223]
	v_pk_mul_f32 v[228:229], v[226:227], v[228:229]
	v_pk_mul_f32 v[222:223], v[224:225], v[222:223]
	v_pk_mul_f32 v[228:229], v[230:231], v[228:229]
	v_max_f32_e32 v220, 0, v138
	v_max_f32_e32 v221, 0, v139
	v_max_f32_e32 v226, 0, v162
	v_max_f32_e32 v227, 0, v163
	v_fma_f32 v138, -|v138|, v222, v220
	v_fma_f32 v139, -|v139|, v223, v221
	v_fma_f32 v162, -|v162|, v228, v226
	v_fma_f32 v163, -|v163|, v229, v227
; __device__ __forceinline__ unsigned pk_bf16(float lo, float hi) { f32x2 v = {lo, hi}; bf16x2_t b = __builtin_convertvector(v, bf16x2_t); return __builtin_bit_cast(unsigned, b); }
; __device__ __forceinline__ f32x4 gelu4(f32x4 v) { f32x2 a = gelu_pk((f32x2){v[0], v[1]}), b = gelu_pk((f32x2){v[2], v[3]}); return (f32x4){a.x, a.y, b.x, b.y}; }
; __device__ __forceinline__ f32x2 gelu_pk(f32x2 v) {
;     const f32x2 av = __builtin_elementwise_abs(v), d = av * 0.2316418882f + 1.0f;
;     f32x2 t; t.x = __builtin_amdgcn_rcpf(d.x); t.y = __builtin_amdgcn_rcpf(d.y);
;     f32x2 q = t * 0.5307027145f + (-0.7265760135f); q = q * t + 0.7107068705f; q = q * t + (-0.142248368f); q = q * t + 0.127414796f; q = q * t;
;     const f32x2 s = (v * v) * (-0.72134752044f);
;     f32x2 e; e.x = __builtin_amdgcn_exp2f(s.x); e.y = __builtin_amdgcn_exp2f(s.y);
;     const f32x2 m = v * (q * e), r = v - m;
;     f32x2 o; o.x = v.x < 0.f ? m.x : r.x; o.y = v.y < 0.f ? m.y : r.y; return o;
;     __device__ __forceinline__ void operator()(const f32x4 (&acc)[2][2][4][2], const Unit& u, int wr, int wc, int fr, int fq, float rp0, float rp1, const f32x4& raw0, const f32x4& raw1, float& rn0, float& rn1) const {
;     ...
;                 for (int k = 0; k < 4; ++k) rs[k] = __shfl(ai ? rp1 : rp0, fr + 16 * k);
; #pragma unroll
;                 for (int m = 0; m < 4; ++m) {
;                     const int roff = ai * HALF + m * 16; const float r = rs[m];
; #pragma unroll
;                     for (int bj = 0; bj < 2; ++bj) {
;                         f32x4 v0 = acc[ai][bj][m][0] * r, v1 = acc[ai][bj][m][1] * r;
;                         if (gel) { v0 = gelu4(v0); v1 = gelu4(v1); }
;                         u32x4 w; w.x = pk_bf16(v0[0], v0[1]); w.y = pk_bf16(v0[2], v0[3]); w.z = pk_bf16(v1[0], v1[1]); w.w = pk_bf16(v1[2], v1[3]);
;                         *(u32x4*)(base + (size_t)roff * ld + bj * 32) = w;
.LBB0_148:
	v_or_b32_e32 v168, 64, v170
	v_or_b32_e32 v169, 0x80, v170
	v_or_b32_e32 v171, 0xc0, v170
	v_cvt_pk_bf16_f32 v167, v162, v163
	ds_bpermute_b32 v162, v170, v154
	v_cvt_pk_bf16_f32 v164, v158, v159
	v_cvt_pk_bf16_f32 v165, v140, v141
	v_cvt_pk_bf16_f32 v166, v138, v139
	ds_bpermute_b32 v158, v168, v154
	ds_bpermute_b32 v140, v169, v154
	ds_bpermute_b32 v138, v171, v154
	global_store_dwordx4 v[160:161], v[164:167], off offset:64
	s_waitcnt lgkmcnt(0)
	v_pk_mul_f32 v[168:169], v[48:49], v[162:163] op_sel_hi:[1,0]
	s_and_b64 vcc, exec, s[6:7]
	v_pk_mul_f32 v[164:165], v[44:45], v[162:163] op_sel_hi:[1,0]
	v_pk_mul_f32 v[166:167], v[42:43], v[162:163] op_sel_hi:[1,0]
	v_pk_mul_f32 v[170:171], v[46:47], v[162:163] op_sel_hi:[1,0]
	s_cbranch_vccnz .LBB0_150
	v_mov_b32_e32 v232, s68
	v_fma_f32 v220, |v166|, s88, 1.0
	v_fma_f32 v221, |v167|, s88, 1.0
	v_fma_f32 v226, |v164|, s88, 1.0
	v_fma_f32 v227, |v165|, s88, 1.0
	v_pk_mul_f32 v[224:225], v[166:167], v[166:167]
	v_pk_mul_f32 v[230:231], v[164:165], v[164:165]
	v_rcp_f32_e32 v220, v220
	v_rcp_f32_e32 v221, v221
	v_rcp_f32_e32 v226, v226
	v_rcp_f32_e32 v227, v227
	v_pk_mul_f32 v[224:225], v[224:225], s[72:73] op_sel_hi:[1,0]
	v_pk_mul_f32 v[230:231], v[230:231], s[72:73] op_sel_hi:[1,0]
	v_pk_fma_f32 v[222:223], v[220:221], s[90:91], v[232:233] op_sel_hi:[1,0,0]
	v_pk_fma_f32 v[228:229], v[226:227], s[90:91], v[232:233] op_sel_hi:[1,0,0]
	v_exp_f32_e32 v224, v224
	v_exp_f32_e32 v225, v225
	v_exp_f32_e32 v230, v230
	v_exp_f32_e32 v231, v231
	v_pk_fma_f32 v[222:223], v[220:221], v[222:223], s[94:95] op_sel_hi:[1,1,0]
	v_pk_fma_f32 v[228:229], v[226:227], v[228:229], s[94:95] op_sel_hi:[1,1,0]
	v_pk_fma_f32 v[222:223], v[220:221], v[222:223], s[96:97] op_sel_hi:[1,1,0]
	v_pk_fma_f32 v[228:229], v[226:227], v[228:229], s[96:97] op_sel_hi:[1,1,0]
	v_pk_fma_f32 v[222:223], v[220:221], v[222:223], s[98:99] op_sel_hi:[1,1,0]
	v_pk_fma_f32 v[228:229], v[226:227], v[228:229], s[98:99] op_sel_hi:[1,1,0]
	v_pk_mul_f32 v[222:223], v[220:221], v[222:223]
	v_pk_mul_f32 v[228:229], v[226:227], v[228:229]
	v_pk_mul_f32 v[222:223], v[224:225], v[222:223]
	v_pk_mul_f32 v[228:229], v[230:231], v[228:229]
	v_max_f32_e32 v220, 0, v166
	v_max_f32_e32 v221, 0, v167
	v_max_f32_e32 v226, 0, v164
	v_max_f32_e32 v227, 0, v165
	v_fma_f32 v166, -|v166|, v222, v220
	v_fma_f32 v167, -|v167|, v223, v221
	v_fma_f32 v164, -|v164|, v228, v226
	v_fma_f32 v165, -|v165|, v229, v227
	v_fma_f32 v220, |v170|, s88, 1.0
	v_fma_f32 v221, |v171|, s88, 1.0
	v_fma_f32 v226, |v168|, s88, 1.0
	v_fma_f32 v227, |v169|, s88, 1.0
	v_pk_mul_f32 v[224:225], v[170:171], v[170:171]
	v_pk_mul_f32 v[230:231], v[168:169], v[168:169]
	v_rcp_f32_e32 v220, v220
	v_rcp_f32_e32 v221, v221
	v_rcp_f32_e32 v226, v226
	v_rcp_f32_e32 v227, v227
	v_pk_mul_f32 v[224:225], v[224:225], s[72:73] op_sel_hi:[1,0]
	v_pk_mul_f32 v[230:231], v[230:231], s[72:73] op_sel_hi:[1,0]
	v_pk_fma_f32 v[222:223], v[220:221], s[90:91], v[232:233] op_sel_hi:[1,0,0]
	v_pk_fma_f32 v[228:229], v[226:227], s[90:91], v[232:233] op_sel_hi:[1,0,0]
	v_exp_f32_e32 v224, v224
	v_exp_f32_e32 v225, v225
	v_exp_f32_e32 v230, v230
	v_exp_f32_e32 v231, v231
	v_pk_fma_f32 v[222:223], v[220:221], v[222:223], s[94:95] op_sel_hi:[1,1,0]
	v_pk_fma_f32 v[228:229], v[226:227], v[228:229], s[94:95] op_sel_hi:[1,1,0]
	v_pk_fma_f32 v[222:223], v[220:221], v[222:223], s[96:97] op_sel_hi:[1,1,0]
	v_pk_fma_f32 v[228:229], v[226:227], v[228:229], s[96:97] op_sel_hi:[1,1,0]
	v_pk_fma_f32 v[222:223], v[220:221], v[222:223], s[98:99] op_sel_hi:[1,1,0]
	v_pk_fma_f32 v[228:229], v[226:227], v[228:229], s[98:99] op_sel_hi:[1,1,0]
	v_pk_mul_f32 v[222:223], v[220:221], v[222:223]
	v_pk_mul_f32 v[228:229], v[226:227], v[228:229]
	v_pk_mul_f32 v[222:223], v[224:225], v[222:223]
	v_pk_mul_f32 v[228:229], v[230:231], v[228:229]
	v_max_f32_e32 v220, 0, v170
	v_max_f32_e32 v221, 0, v171
	v_max_f32_e32 v226, 0, v168
	v_max_f32_e32 v227, 0, v169
	v_fma_f32 v170, -|v170|, v222, v220
	v_fma_f32 v171, -|v171|, v223, v221
	v_fma_f32 v168, -|v168|, v228, v226
	v_fma_f32 v169, -|v169|, v229, v227
.LBB0_150:
	v_mov_b32_e32 v163, v162
	v_cvt_pk_bf16_f32 v177, v168, v169
	v_mov_b32_e32 v168, v162
	v_mov_b32_e32 v169, v162
	v_mad_u64_u32 v[160:161], s[40:41], s10, v217, v[160:161]
	v_cvt_pk_bf16_f32 v174, v166, v167
	v_cvt_pk_bf16_f32 v175, v164, v165
	v_cvt_pk_bf16_f32 v176, v170, v171
	v_pk_mul_f32 v[164:165], v[60:61], v[168:169]
	v_pk_mul_f32 v[166:167], v[58:59], v[162:163]
	v_pk_mul_f32 v[168:169], v[64:65], v[168:169]
	s_and_b64 vcc, exec, s[6:7]
	v_pk_mul_f32 v[162:163], v[62:63], v[162:163]
	global_store_dwordx4 v[160:161], v[174:177], off
	s_cbranch_vccnz .LBB0_152
; __device__ __forceinline__ unsigned pk_bf16(float lo, float hi) { f32x2 v = {lo, hi}; bf16x2_t b = __builtin_convertvector(v, bf16x2_t); return __builtin_bit_cast(unsigned, b); }
; __device__ __forceinline__ f32x4 gelu4(f32x4 v) { f32x2 a = gelu_pk((f32x2){v[0], v[1]}), b = gelu_pk((f32x2){v[2], v[3]}); return (f32x4){a.x, a.y, b.x, b.y}; }
; __device__ __forceinline__ f32x2 gelu_pk(f32x2 v) {
;     const f32x2 av = __builtin_elementwise_abs(v), d = av * 0.2316418882f + 1.0f;
;     f32x2 t; t.x = __builtin_amdgcn_rcpf(d.x); t.y = __builtin_amdgcn_rcpf(d.y);
;     f32x2 q = t * 0.5307027145f + (-0.7265760135f); q = q * t + 0.7107068705f; q = q * t + (-0.142248368f); q = q * t + 0.127414796f; q = q * t;
;     const f32x2 s = (v * v) * (-0.72134752044f);
;     f32x2 e; e.x = __builtin_amdgcn_exp2f(s.x); e.y = __builtin_amdgcn_exp2f(s.y);
;     const f32x2 m = v * (q * e), r = v - m;
;     f32x2 o; o.x = v.x < 0.f ? m.x : r.x; o.y = v.y < 0.f ? m.y : r.y; return o;
;     __device__ __forceinline__ void operator()(const f32x4 (&acc)[2][2][4][2], const Unit& u, int wr, int wc, int fr, int fq, float rp0, float rp1, const f32x4& raw0, const f32x4& raw1, float& rn0, float& rn1) const {
;     ...
;                         f32x4 v0 = acc[ai][bj][m][0] * r, v1 = acc[ai][bj][m][1] * r;
;                         if (gel) { v0 = gelu4(v0); v1 = gelu4(v1); }
;                         u32x4 w; w.x = pk_bf16(v0[0], v0[1]); w.y = pk_bf16(v0[2], v0[3]); w.z = pk_bf16(v1[0], v1[1]); w.w = pk_bf16(v1[2], v1[3]);
;                         *(u32x4*)(base + (size_t)roff * ld + bj * 32) = w;
	v_mov_b32_e32 v232, s68
	v_fma_f32 v220, |v166|, s88, 1.0
	v_fma_f32 v221, |v167|, s88, 1.0
	v_fma_f32 v226, |v164|, s88, 1.0
	v_fma_f32 v227, |v165|, s88, 1.0
	v_pk_mul_f32 v[224:225], v[166:167], v[166:167]
	v_pk_mul_f32 v[230:231], v[164:165], v[164:165]
	v_rcp_f32_e32 v220, v220
	v_rcp_f32_e32 v221, v221
	v_rcp_f32_e32 v226, v226
	v_rcp_f32_e32 v227, v227
	v_pk_mul_f32 v[224:225], v[224:225], s[72:73] op_sel_hi:[1,0]
	v_pk_mul_f32 v[230:231], v[230:231], s[72:73] op_sel_hi:[1,0]
	v_pk_fma_f32 v[222:223], v[220:221], s[90:91], v[232:233] op_sel_hi:[1,0,0]
	v_pk_fma_f32 v[228:229], v[226:227], s[90:91], v[232:233] op_sel_hi:[1,0,0]
	v_exp_f32_e32 v224, v224
	v_exp_f32_e32 v225, v225
	v_exp_f32_e32 v230, v230
	v_exp_f32_e32 v231, v231
	v_pk_fma_f32 v[222:223], v[220:221], v[222:223], s[94:95] op_sel_hi:[1,1,0]
	v_pk_fma_f32 v[228:229], v[226:227], v[228:229], s[94:95] op_sel_hi:[1,1,0]
	v_pk_fma_f32 v[222:223], v[220:221], v[222:223], s[96:97] op_sel_hi:[1,1,0]
	v_pk_fma_f32 v[228:229], v[226:227], v[228:229], s[96:97] op_sel_hi:[1,1,0]
	v_pk_fma_f32 v[222:223], v[220:221], v[222:223], s[98:99] op_sel_hi:[1,1,0]
	v_pk_fma_f32 v[228:229], v[226:227], v[228:229], s[98:99] op_sel_hi:[1,1,0]
	v_pk_mul_f32 v[222:223], v[220:221], v[222:223]
	v_pk_mul_f32 v[228:229], v[226:227], v[228:229]
	v_pk_mul_f32 v[222:223], v[224:225], v[222:223]
	v_pk_mul_f32 v[228:229], v[230:231], v[228:229]
	v_max_f32_e32 v220, 0, v166
	v_max_f32_e32 v221, 0, v167
	v_max_f32_e32 v226, 0, v164
	v_max_f32_e32 v227, 0, v165
	v_fma_f32 v166, -|v166|, v222, v220
	v_fma_f32 v167, -|v167|, v223, v221
	v_fma_f32 v164, -|v164|, v228, v226
	v_fma_f32 v165, -|v165|, v229, v227
	v_fma_f32 v220, |v162|, s88, 1.0
	v_fma_f32 v221, |v163|, s88, 1.0
	v_fma_f32 v226, |v168|, s88, 1.0
	v_fma_f32 v227, |v169|, s88, 1.0
	v_pk_mul_f32 v[224:225], v[162:163], v[162:163]
	v_pk_mul_f32 v[230:231], v[168:169], v[168:169]
	v_rcp_f32_e32 v220, v220
	v_rcp_f32_e32 v221, v221
	v_rcp_f32_e32 v226, v226
	v_rcp_f32_e32 v227, v227
	v_pk_mul_f32 v[224:225], v[224:225], s[72:73] op_sel_hi:[1,0]
	v_pk_mul_f32 v[230:231], v[230:231], s[72:73] op_sel_hi:[1,0]
	v_pk_fma_f32 v[222:223], v[220:221], s[90:91], v[232:233] op_sel_hi:[1,0,0]
	v_pk_fma_f32 v[228:229], v[226:227], s[90:91], v[232:233] op_sel_hi:[1,0,0]
	v_exp_f32_e32 v224, v224
	v_exp_f32_e32 v225, v225
	v_exp_f32_e32 v230, v230
	v_exp_f32_e32 v231, v231
	v_pk_fma_f32 v[222:223], v[220:221], v[222:223], s[94:95] op_sel_hi:[1,1,0]
	v_pk_fma_f32 v[228:229], v[226:227], v[228:229], s[94:95] op_sel_hi:[1,1,0]
	v_pk_fma_f32 v[222:223], v[220:221], v[222:223], s[96:97] op_sel_hi:[1,1,0]
	v_pk_fma_f32 v[228:229], v[226:227], v[228:229], s[96:97] op_sel_hi:[1,1,0]
	v_pk_fma_f32 v[222:223], v[220:221], v[222:223], s[98:99] op_sel_hi:[1,1,0]
	v_pk_fma_f32 v[228:229], v[226:227], v[228:229], s[98:99] op_sel_hi:[1,1,0]
	v_pk_mul_f32 v[222:223], v[220:221], v[222:223]
	v_pk_mul_f32 v[228:229], v[226:227], v[228:229]
	v_pk_mul_f32 v[222:223], v[224:225], v[222:223]
	v_pk_mul_f32 v[228:229], v[230:231], v[228:229]
	v_max_f32_e32 v220, 0, v162
	v_max_f32_e32 v221, 0, v163
	v_max_f32_e32 v226, 0, v168
	v_max_f32_e32 v227, 0, v169
	v_fma_f32 v162, -|v162|, v222, v220
	v_fma_f32 v163, -|v163|, v223, v221
	v_fma_f32 v168, -|v168|, v228, v226
	v_fma_f32 v169, -|v169|, v229, v227
.LBB0_152:
	s_nop 0
	v_cvt_pk_bf16_f32 v174, v166, v167
	v_cvt_pk_bf16_f32 v175, v164, v165
	v_cvt_pk_bf16_f32 v176, v162, v163
	v_cvt_pk_bf16_f32 v177, v168, v169
	v_pk_mul_f32 v[162:163], v[36:37], v[158:159] op_sel_hi:[1,0]
	v_pk_mul_f32 v[164:165], v[34:35], v[158:159] op_sel_hi:[1,0]
	v_pk_mul_f32 v[166:167], v[40:41], v[158:159] op_sel_hi:[1,0]
	s_and_b64 vcc, exec, s[6:7]
	v_pk_mul_f32 v[168:169], v[38:39], v[158:159] op_sel_hi:[1,0]
	global_store_dwordx4 v[160:161], v[174:177], off offset:64
	s_cbranch_vccnz .LBB0_154
	v_mov_b32_e32 v232, s68
	v_fma_f32 v220, |v164|, s88, 1.0
	v_fma_f32 v221, |v165|, s88, 1.0
	v_fma_f32 v226, |v162|, s88, 1.0
	v_fma_f32 v227, |v163|, s88, 1.0
	v_pk_mul_f32 v[224:225], v[164:165], v[164:165]
	v_pk_mul_f32 v[230:231], v[162:163], v[162:163]
	v_rcp_f32_e32 v220, v220
	v_rcp_f32_e32 v221, v221
	v_rcp_f32_e32 v226, v226
	v_rcp_f32_e32 v227, v227
	v_pk_mul_f32 v[224:225], v[224:225], s[72:73] op_sel_hi:[1,0]
	v_pk_mul_f32 v[230:231], v[230:231], s[72:73] op_sel_hi:[1,0]
	v_pk_fma_f32 v[222:223], v[220:221], s[90:91], v[232:233] op_sel_hi:[1,0,0]
	v_pk_fma_f32 v[228:229], v[226:227], s[90:91], v[232:233] op_sel_hi:[1,0,0]
	v_exp_f32_e32 v224, v224
	v_exp_f32_e32 v225, v225
	v_exp_f32_e32 v230, v230
	v_exp_f32_e32 v231, v231
	v_pk_fma_f32 v[222:223], v[220:221], v[222:223], s[94:95] op_sel_hi:[1,1,0]
	v_pk_fma_f32 v[228:229], v[226:227], v[228:229], s[94:95] op_sel_hi:[1,1,0]
	v_pk_fma_f32 v[222:223], v[220:221], v[222:223], s[96:97] op_sel_hi:[1,1,0]
	v_pk_fma_f32 v[228:229], v[226:227], v[228:229], s[96:97] op_sel_hi:[1,1,0]
	v_pk_fma_f32 v[222:223], v[220:221], v[222:223], s[98:99] op_sel_hi:[1,1,0]
	v_pk_fma_f32 v[228:229], v[226:227], v[228:229], s[98:99] op_sel_hi:[1,1,0]
	v_pk_mul_f32 v[222:223], v[220:221], v[222:223]
	v_pk_mul_f32 v[228:229], v[226:227], v[228:229]
	v_pk_mul_f32 v[222:223], v[224:225], v[222:223]
	v_pk_mul_f32 v[228:229], v[230:231], v[228:229]
	v_max_f32_e32 v220, 0, v164
	v_max_f32_e32 v221, 0, v165
	v_max_f32_e32 v226, 0, v162
	v_max_f32_e32 v227, 0, v163
	v_fma_f32 v164, -|v164|, v222, v220
	v_fma_f32 v165, -|v165|, v223, v221
	v_fma_f32 v162, -|v162|, v228, v226
	v_fma_f32 v163, -|v163|, v229, v227
	v_fma_f32 v220, |v168|, s88, 1.0
	v_fma_f32 v221, |v169|, s88, 1.0
	v_fma_f32 v226, |v166|, s88, 1.0
	v_fma_f32 v227, |v167|, s88, 1.0
; __device__ __forceinline__ unsigned pk_bf16(float lo, float hi) { f32x2 v = {lo, hi}; bf16x2_t b = __builtin_convertvector(v, bf16x2_t); return __builtin_bit_cast(unsigned, b); }
; __device__ __forceinline__ f32x4 gelu4(f32x4 v) { f32x2 a = gelu_pk((f32x2){v[0], v[1]}), b = gelu_pk((f32x2){v[2], v[3]}); return (f32x4){a.x, a.y, b.x, b.y}; }
; __device__ __forceinline__ f32x2 gelu_pk(f32x2 v) {
;     const f32x2 av = __builtin_elementwise_abs(v), d = av * 0.2316418882f + 1.0f;
;     f32x2 t; t.x = __builtin_amdgcn_rcpf(d.x); t.y = __builtin_amdgcn_rcpf(d.y);
;     f32x2 q = t * 0.5307027145f + (-0.7265760135f); q = q * t + 0.7107068705f; q = q * t + (-0.142248368f); q = q * t + 0.127414796f; q = q * t;
;     const f32x2 s = (v * v) * (-0.72134752044f);
;     f32x2 e; e.x = __builtin_amdgcn_exp2f(s.x); e.y = __builtin_amdgcn_exp2f(s.y);
;     const f32x2 m = v * (q * e), r = v - m;
;     f32x2 o; o.x = v.x < 0.f ? m.x : r.x; o.y = v.y < 0.f ? m.y : r.y; return o;
;     __device__ __forceinline__ void operator()(const f32x4 (&acc)[2][2][4][2], const Unit& u, int wr, int wc, int fr, int fq, float rp0, float rp1, const f32x4& raw0, const f32x4& raw1, float& rn0, float& rn1) const {
;     ...
;                         f32x4 v0 = acc[ai][bj][m][0] * r, v1 = acc[ai][bj][m][1] * r;
;                         if (gel) { v0 = gelu4(v0); v1 = gelu4(v1); }
;                         u32x4 w; w.x = pk_bf16(v0[0], v0[1]); w.y = pk_bf16(v0[2], v0[3]); w.z = pk_bf16(v1[0], v1[1]); w.w = pk_bf16(v1[2], v1[3]);
;                         *(u32x4*)(base + (size_t)roff * ld + bj * 32) = w;
	v_pk_mul_f32 v[224:225], v[168:169], v[168:169]
	v_pk_mul_f32 v[230:231], v[166:167], v[166:167]
	v_rcp_f32_e32 v220, v220
	v_rcp_f32_e32 v221, v221
	v_rcp_f32_e32 v226, v226
	v_rcp_f32_e32 v227, v227
	v_pk_mul_f32 v[224:225], v[224:225], s[72:73] op_sel_hi:[1,0]
	v_pk_mul_f32 v[230:231], v[230:231], s[72:73] op_sel_hi:[1,0]
	v_pk_fma_f32 v[222:223], v[220:221], s[90:91], v[232:233] op_sel_hi:[1,0,0]
	v_pk_fma_f32 v[228:229], v[226:227], s[90:91], v[232:233] op_sel_hi:[1,0,0]
	v_exp_f32_e32 v224, v224
	v_exp_f32_e32 v225, v225
	v_exp_f32_e32 v230, v230
	v_exp_f32_e32 v231, v231
	v_pk_fma_f32 v[222:223], v[220:221], v[222:223], s[94:95] op_sel_hi:[1,1,0]
	v_pk_fma_f32 v[228:229], v[226:227], v[228:229], s[94:95] op_sel_hi:[1,1,0]
	v_pk_fma_f32 v[222:223], v[220:221], v[222:223], s[96:97] op_sel_hi:[1,1,0]
	v_pk_fma_f32 v[228:229], v[226:227], v[228:229], s[96:97] op_sel_hi:[1,1,0]
	v_pk_fma_f32 v[222:223], v[220:221], v[222:223], s[98:99] op_sel_hi:[1,1,0]
	v_pk_fma_f32 v[228:229], v[226:227], v[228:229], s[98:99] op_sel_hi:[1,1,0]
	v_pk_mul_f32 v[222:223], v[220:221], v[222:223]
	v_pk_mul_f32 v[228:229], v[226:227], v[228:229]
	v_pk_mul_f32 v[222:223], v[224:225], v[222:223]
	v_pk_mul_f32 v[228:229], v[230:231], v[228:229]
	v_max_f32_e32 v220, 0, v168
	v_max_f32_e32 v221, 0, v169
	v_max_f32_e32 v226, 0, v166
	v_max_f32_e32 v227, 0, v167
	v_fma_f32 v168, -|v168|, v222, v220
	v_fma_f32 v169, -|v169|, v223, v221
	v_fma_f32 v166, -|v166|, v228, v226
	v_fma_f32 v167, -|v167|, v229, v227
.LBB0_154:
	v_mov_b32_e32 v159, v158
	v_cvt_pk_bf16_f32 v177, v166, v167
	v_mov_b32_e32 v166, v158
	v_mov_b32_e32 v167, v158
	v_lshl_add_u64 v[160:161], v[160:161], 0, s[76:77]
	v_cvt_pk_bf16_f32 v174, v164, v165
	v_cvt_pk_bf16_f32 v175, v162, v163
	v_cvt_pk_bf16_f32 v176, v168, v169
	v_pk_mul_f32 v[162:163], v[52:53], v[166:167]
	v_pk_mul_f32 v[164:165], v[50:51], v[158:159]
	v_pk_mul_f32 v[166:167], v[56:57], v[166:167]
	s_and_b64 vcc, exec, s[6:7]
	v_pk_mul_f32 v[158:159], v[54:55], v[158:159]
	global_store_dwordx4 v[160:161], v[174:177], off
	s_cbranch_vccnz .LBB0_156
	v_mov_b32_e32 v232, s68
	v_fma_f32 v220, |v164|, s88, 1.0
	v_fma_f32 v221, |v165|, s88, 1.0
	v_fma_f32 v226, |v162|, s88, 1.0
	v_fma_f32 v227, |v163|, s88, 1.0
	v_pk_mul_f32 v[224:225], v[164:165], v[164:165]
	v_pk_mul_f32 v[230:231], v[162:163], v[162:163]
	v_rcp_f32_e32 v220, v220
	v_rcp_f32_e32 v221, v221
	v_rcp_f32_e32 v226, v226
	v_rcp_f32_e32 v227, v227
	v_pk_mul_f32 v[224:225], v[224:225], s[72:73] op_sel_hi:[1,0]
	v_pk_mul_f32 v[230:231], v[230:231], s[72:73] op_sel_hi:[1,0]
	v_pk_fma_f32 v[222:223], v[220:221], s[90:91], v[232:233] op_sel_hi:[1,0,0]
	v_pk_fma_f32 v[228:229], v[226:227], s[90:91], v[232:233] op_sel_hi:[1,0,0]
	v_exp_f32_e32 v224, v224
	v_exp_f32_e32 v225, v225
	v_exp_f32_e32 v230, v230
	v_exp_f32_e32 v231, v231
	v_pk_fma_f32 v[222:223], v[220:221], v[222:223], s[94:95] op_sel_hi:[1,1,0]
	v_pk_fma_f32 v[228:229], v[226:227], v[228:229], s[94:95] op_sel_hi:[1,1,0]
	v_pk_fma_f32 v[222:223], v[220:221], v[222:223], s[96:97] op_sel_hi:[1,1,0]
	v_pk_fma_f32 v[228:229], v[226:227], v[228:229], s[96:97] op_sel_hi:[1,1,0]
	v_pk_fma_f32 v[222:223], v[220:221], v[222:223], s[98:99] op_sel_hi:[1,1,0]
	v_pk_fma_f32 v[228:229], v[226:227], v[228:229], s[98:99] op_sel_hi:[1,1,0]
	v_pk_mul_f32 v[222:223], v[220:221], v[222:223]
	v_pk_mul_f32 v[228:229], v[226:227], v[228:229]
	v_pk_mul_f32 v[222:223], v[224:225], v[222:223]
	v_pk_mul_f32 v[228:229], v[230:231], v[228:229]
	v_max_f32_e32 v220, 0, v164
	v_max_f32_e32 v221, 0, v165
	v_max_f32_e32 v226, 0, v162
	v_max_f32_e32 v227, 0, v163
	v_fma_f32 v164, -|v164|, v222, v220
	v_fma_f32 v165, -|v165|, v223, v221
	v_fma_f32 v162, -|v162|, v228, v226
	v_fma_f32 v163, -|v163|, v229, v227
	v_fma_f32 v220, |v158|, s88, 1.0
	v_fma_f32 v221, |v159|, s88, 1.0
	v_fma_f32 v226, |v166|, s88, 1.0
	v_fma_f32 v227, |v167|, s88, 1.0
	v_pk_mul_f32 v[224:225], v[158:159], v[158:159]
	v_pk_mul_f32 v[230:231], v[166:167], v[166:167]
	v_rcp_f32_e32 v220, v220
	v_rcp_f32_e32 v221, v221
	v_rcp_f32_e32 v226, v226
	v_rcp_f32_e32 v227, v227
	v_pk_mul_f32 v[224:225], v[224:225], s[72:73] op_sel_hi:[1,0]
	v_pk_mul_f32 v[230:231], v[230:231], s[72:73] op_sel_hi:[1,0]
	v_pk_fma_f32 v[222:223], v[220:221], s[90:91], v[232:233] op_sel_hi:[1,0,0]
	v_pk_fma_f32 v[228:229], v[226:227], s[90:91], v[232:233] op_sel_hi:[1,0,0]
	v_exp_f32_e32 v224, v224
	v_exp_f32_e32 v225, v225
	v_exp_f32_e32 v230, v230
	v_exp_f32_e32 v231, v231
	v_pk_fma_f32 v[222:223], v[220:221], v[222:223], s[94:95] op_sel_hi:[1,1,0]
	v_pk_fma_f32 v[228:229], v[226:227], v[228:229], s[94:95] op_sel_hi:[1,1,0]
	v_pk_fma_f32 v[222:223], v[220:221], v[222:223], s[96:97] op_sel_hi:[1,1,0]
	v_pk_fma_f32 v[228:229], v[226:227], v[228:229], s[96:97] op_sel_hi:[1,1,0]
	v_pk_fma_f32 v[222:223], v[220:221], v[222:223], s[98:99] op_sel_hi:[1,1,0]
	v_pk_fma_f32 v[228:229], v[226:227], v[228:229], s[98:99] op_sel_hi:[1,1,0]
	v_pk_mul_f32 v[222:223], v[220:221], v[222:223]
	v_pk_mul_f32 v[228:229], v[226:227], v[228:229]
	v_pk_mul_f32 v[222:223], v[224:225], v[222:223]
	v_pk_mul_f32 v[228:229], v[230:231], v[228:229]
	v_max_f32_e32 v220, 0, v158
	v_max_f32_e32 v221, 0, v159
	v_max_f32_e32 v226, 0, v166
	v_max_f32_e32 v227, 0, v167
	v_fma_f32 v158, -|v158|, v222, v220
	v_fma_f32 v159, -|v159|, v223, v221
	v_fma_f32 v166, -|v166|, v228, v226
	v_fma_f32 v167, -|v167|, v229, v227
; __device__ __forceinline__ unsigned pk_bf16(float lo, float hi) { f32x2 v = {lo, hi}; bf16x2_t b = __builtin_convertvector(v, bf16x2_t); return __builtin_bit_cast(unsigned, b); }
; __device__ __forceinline__ f32x4 gelu4(f32x4 v) { f32x2 a = gelu_pk((f32x2){v[0], v[1]}), b = gelu_pk((f32x2){v[2], v[3]}); return (f32x4){a.x, a.y, b.x, b.y}; }
; __device__ __forceinline__ f32x2 gelu_pk(f32x2 v) {
;     const f32x2 av = __builtin_elementwise_abs(v), d = av * 0.2316418882f + 1.0f;
;     f32x2 t; t.x = __builtin_amdgcn_rcpf(d.x); t.y = __builtin_amdgcn_rcpf(d.y);
;     f32x2 q = t * 0.5307027145f + (-0.7265760135f); q = q * t + 0.7107068705f; q = q * t + (-0.142248368f); q = q * t + 0.127414796f; q = q * t;
;     const f32x2 s = (v * v) * (-0.72134752044f);
;     f32x2 e; e.x = __builtin_amdgcn_exp2f(s.x); e.y = __builtin_amdgcn_exp2f(s.y);
;     const f32x2 m = v * (q * e), r = v - m;
;     f32x2 o; o.x = v.x < 0.f ? m.x : r.x; o.y = v.y < 0.f ? m.y : r.y; return o;
;     __device__ __forceinline__ void operator()(const f32x4 (&acc)[2][2][4][2], const Unit& u, int wr, int wc, int fr, int fq, float rp0, float rp1, const f32x4& raw0, const f32x4& raw1, float& rn0, float& rn1) const {
;     ...
;                         f32x4 v0 = acc[ai][bj][m][0] * r, v1 = acc[ai][bj][m][1] * r;
;                         if (gel) { v0 = gelu4(v0); v1 = gelu4(v1); }
;                         u32x4 w; w.x = pk_bf16(v0[0], v0[1]); w.y = pk_bf16(v0[2], v0[3]); w.z = pk_bf16(v1[0], v1[1]); w.w = pk_bf16(v1[2], v1[3]);
;                         *(u32x4*)(base + (size_t)roff * ld + bj * 32) = w;
.LBB0_156:
	v_cvt_pk_bf16_f32 v168, v164, v165
	v_cvt_pk_bf16_f32 v169, v162, v163
	v_cvt_pk_bf16_f32 v170, v158, v159
	v_cvt_pk_bf16_f32 v171, v166, v167
	global_store_dwordx4 v[160:161], v[168:171], off offset:64
	v_pk_mul_f32 v[162:163], v[12:13], v[140:141] op_sel_hi:[1,0]
	v_pk_mul_f32 v[164:165], v[10:11], v[140:141] op_sel_hi:[1,0]
	v_pk_mul_f32 v[166:167], v[16:17], v[140:141] op_sel_hi:[1,0]
	s_and_b64 vcc, exec, s[6:7]
	v_pk_mul_f32 v[168:169], v[14:15], v[140:141] op_sel_hi:[1,0]
	s_cbranch_vccnz .LBB0_158
	v_mov_b32_e32 v232, s68
	v_fma_f32 v220, |v164|, s88, 1.0
	v_fma_f32 v221, |v165|, s88, 1.0
	v_fma_f32 v226, |v162|, s88, 1.0
	v_fma_f32 v227, |v163|, s88, 1.0
	v_pk_mul_f32 v[224:225], v[164:165], v[164:165]
	v_pk_mul_f32 v[230:231], v[162:163], v[162:163]
	v_rcp_f32_e32 v220, v220
	v_rcp_f32_e32 v221, v221
	v_rcp_f32_e32 v226, v226
	v_rcp_f32_e32 v227, v227
	v_pk_mul_f32 v[224:225], v[224:225], s[72:73] op_sel_hi:[1,0]
	v_pk_mul_f32 v[230:231], v[230:231], s[72:73] op_sel_hi:[1,0]
	v_pk_fma_f32 v[222:223], v[220:221], s[90:91], v[232:233] op_sel_hi:[1,0,0]
	v_pk_fma_f32 v[228:229], v[226:227], s[90:91], v[232:233] op_sel_hi:[1,0,0]
	v_exp_f32_e32 v224, v224
	v_exp_f32_e32 v225, v225
	v_exp_f32_e32 v230, v230
	v_exp_f32_e32 v231, v231
	v_pk_fma_f32 v[222:223], v[220:221], v[222:223], s[94:95] op_sel_hi:[1,1,0]
	v_pk_fma_f32 v[228:229], v[226:227], v[228:229], s[94:95] op_sel_hi:[1,1,0]
	v_pk_fma_f32 v[222:223], v[220:221], v[222:223], s[96:97] op_sel_hi:[1,1,0]
	v_pk_fma_f32 v[228:229], v[226:227], v[228:229], s[96:97] op_sel_hi:[1,1,0]
	v_pk_fma_f32 v[222:223], v[220:221], v[222:223], s[98:99] op_sel_hi:[1,1,0]
	v_pk_fma_f32 v[228:229], v[226:227], v[228:229], s[98:99] op_sel_hi:[1,1,0]
	v_pk_mul_f32 v[222:223], v[220:221], v[222:223]
	v_pk_mul_f32 v[228:229], v[226:227], v[228:229]
	v_pk_mul_f32 v[222:223], v[224:225], v[222:223]
	v_pk_mul_f32 v[228:229], v[230:231], v[228:229]
	v_max_f32_e32 v220, 0, v164
	v_max_f32_e32 v221, 0, v165
	v_max_f32_e32 v226, 0, v162
	v_max_f32_e32 v227, 0, v163
	v_fma_f32 v164, -|v164|, v222, v220
	v_fma_f32 v165, -|v165|, v223, v221
	v_fma_f32 v162, -|v162|, v228, v226
	v_fma_f32 v163, -|v163|, v229, v227
	v_fma_f32 v220, |v168|, s88, 1.0
	v_fma_f32 v221, |v169|, s88, 1.0
	v_fma_f32 v226, |v166|, s88, 1.0
	v_fma_f32 v227, |v167|, s88, 1.0
	v_pk_mul_f32 v[224:225], v[168:169], v[168:169]
	v_pk_mul_f32 v[230:231], v[166:167], v[166:167]
	v_rcp_f32_e32 v220, v220
	v_rcp_f32_e32 v221, v221
	v_rcp_f32_e32 v226, v226
	v_rcp_f32_e32 v227, v227
	v_pk_mul_f32 v[224:225], v[224:225], s[72:73] op_sel_hi:[1,0]
	v_pk_mul_f32 v[230:231], v[230:231], s[72:73] op_sel_hi:[1,0]
	v_pk_fma_f32 v[222:223], v[220:221], s[90:91], v[232:233] op_sel_hi:[1,0,0]
	v_pk_fma_f32 v[228:229], v[226:227], s[90:91], v[232:233] op_sel_hi:[1,0,0]
	v_exp_f32_e32 v224, v224
	v_exp_f32_e32 v225, v225
	v_exp_f32_e32 v230, v230
	v_exp_f32_e32 v231, v231
	v_pk_fma_f32 v[222:223], v[220:221], v[222:223], s[94:95] op_sel_hi:[1,1,0]
	v_pk_fma_f32 v[228:229], v[226:227], v[228:229], s[94:95] op_sel_hi:[1,1,0]
	v_pk_fma_f32 v[222:223], v[220:221], v[222:223], s[96:97] op_sel_hi:[1,1,0]
	v_pk_fma_f32 v[228:229], v[226:227], v[228:229], s[96:97] op_sel_hi:[1,1,0]
	v_pk_fma_f32 v[222:223], v[220:221], v[222:223], s[98:99] op_sel_hi:[1,1,0]
	v_pk_fma_f32 v[228:229], v[226:227], v[228:229], s[98:99] op_sel_hi:[1,1,0]
	v_pk_mul_f32 v[222:223], v[220:221], v[222:223]
	v_pk_mul_f32 v[228:229], v[226:227], v[228:229]
	v_pk_mul_f32 v[222:223], v[224:225], v[222:223]
	v_pk_mul_f32 v[228:229], v[230:231], v[228:229]
	v_max_f32_e32 v220, 0, v168
	v_max_f32_e32 v221, 0, v169
	v_max_f32_e32 v226, 0, v166
	v_max_f32_e32 v227, 0, v167
	v_fma_f32 v168, -|v168|, v222, v220
	v_fma_f32 v169, -|v169|, v223, v221
	v_fma_f32 v166, -|v166|, v228, v226
	v_fma_f32 v167, -|v167|, v229, v227
.LBB0_158:
	v_mov_b32_e32 v141, v140
	v_lshl_add_u64 v[158:159], v[160:161], 0, s[76:77]
	v_cvt_pk_bf16_f32 v160, v164, v165
	v_cvt_pk_bf16_f32 v161, v162, v163
	v_cvt_pk_bf16_f32 v162, v168, v169
	v_cvt_pk_bf16_f32 v163, v166, v167
	v_mov_b32_e32 v164, v140
	v_mov_b32_e32 v165, v140
	global_store_dwordx4 v[158:159], v[160:163], off
	s_and_b64 vcc, exec, s[6:7]
	s_nop 0
	v_pk_mul_f32 v[160:161], v[28:29], v[164:165]
	v_pk_mul_f32 v[162:163], v[26:27], v[140:141]
	v_pk_mul_f32 v[164:165], v[32:33], v[164:165]
	v_pk_mul_f32 v[140:141], v[30:31], v[140:141]
	s_cbranch_vccnz .LBB0_160
; __device__ __forceinline__ unsigned pk_bf16(float lo, float hi) { f32x2 v = {lo, hi}; bf16x2_t b = __builtin_convertvector(v, bf16x2_t); return __builtin_bit_cast(unsigned, b); }
; __device__ __forceinline__ f32x4 gelu4(f32x4 v) { f32x2 a = gelu_pk((f32x2){v[0], v[1]}), b = gelu_pk((f32x2){v[2], v[3]}); return (f32x4){a.x, a.y, b.x, b.y}; }
; __device__ __forceinline__ f32x2 gelu_pk(f32x2 v) {
;     const f32x2 av = __builtin_elementwise_abs(v), d = av * 0.2316418882f + 1.0f;
;     f32x2 t; t.x = __builtin_amdgcn_rcpf(d.x); t.y = __builtin_amdgcn_rcpf(d.y);
;     f32x2 q = t * 0.5307027145f + (-0.7265760135f); q = q * t + 0.7107068705f; q = q * t + (-0.142248368f); q = q * t + 0.127414796f; q = q * t;
;     const f32x2 s = (v * v) * (-0.72134752044f);
;     f32x2 e; e.x = __builtin_amdgcn_exp2f(s.x); e.y = __builtin_amdgcn_exp2f(s.y);
;     const f32x2 m = v * (q * e), r = v - m;
;     f32x2 o; o.x = v.x < 0.f ? m.x : r.x; o.y = v.y < 0.f ? m.y : r.y; return o;
;     __device__ __forceinline__ void operator()(const f32x4 (&acc)[2][2][4][2], const Unit& u, int wr, int wc, int fr, int fq, float rp0, float rp1, const f32x4& raw0, const f32x4& raw1, float& rn0, float& rn1) const {
;     ...
;                         f32x4 v0 = acc[ai][bj][m][0] * r, v1 = acc[ai][bj][m][1] * r;
;                         if (gel) { v0 = gelu4(v0); v1 = gelu4(v1); }
;                         u32x4 w; w.x = pk_bf16(v0[0], v0[1]); w.y = pk_bf16(v0[2], v0[3]); w.z = pk_bf16(v1[0], v1[1]); w.w = pk_bf16(v1[2], v1[3]);
;                         *(u32x4*)(base + (size_t)roff * ld + bj * 32) = w;
	v_mov_b32_e32 v232, s68
	v_fma_f32 v220, |v162|, s88, 1.0
	v_fma_f32 v221, |v163|, s88, 1.0
	v_fma_f32 v226, |v160|, s88, 1.0
	v_fma_f32 v227, |v161|, s88, 1.0
	v_pk_mul_f32 v[224:225], v[162:163], v[162:163]
	v_pk_mul_f32 v[230:231], v[160:161], v[160:161]
	v_rcp_f32_e32 v220, v220
	v_rcp_f32_e32 v221, v221
	v_rcp_f32_e32 v226, v226
	v_rcp_f32_e32 v227, v227
	v_pk_mul_f32 v[224:225], v[224:225], s[72:73] op_sel_hi:[1,0]
	v_pk_mul_f32 v[230:231], v[230:231], s[72:73] op_sel_hi:[1,0]
	v_pk_fma_f32 v[222:223], v[220:221], s[90:91], v[232:233] op_sel_hi:[1,0,0]
	v_pk_fma_f32 v[228:229], v[226:227], s[90:91], v[232:233] op_sel_hi:[1,0,0]
	v_exp_f32_e32 v224, v224
	v_exp_f32_e32 v225, v225
	v_exp_f32_e32 v230, v230
	v_exp_f32_e32 v231, v231
	v_pk_fma_f32 v[222:223], v[220:221], v[222:223], s[94:95] op_sel_hi:[1,1,0]
	v_pk_fma_f32 v[228:229], v[226:227], v[228:229], s[94:95] op_sel_hi:[1,1,0]
	v_pk_fma_f32 v[222:223], v[220:221], v[222:223], s[96:97] op_sel_hi:[1,1,0]
	v_pk_fma_f32 v[228:229], v[226:227], v[228:229], s[96:97] op_sel_hi:[1,1,0]
	v_pk_fma_f32 v[222:223], v[220:221], v[222:223], s[98:99] op_sel_hi:[1,1,0]
	v_pk_fma_f32 v[228:229], v[226:227], v[228:229], s[98:99] op_sel_hi:[1,1,0]
	v_pk_mul_f32 v[222:223], v[220:221], v[222:223]
	v_pk_mul_f32 v[228:229], v[226:227], v[228:229]
	v_pk_mul_f32 v[222:223], v[224:225], v[222:223]
	v_pk_mul_f32 v[228:229], v[230:231], v[228:229]
	v_max_f32_e32 v220, 0, v162
	v_max_f32_e32 v221, 0, v163
	v_max_f32_e32 v226, 0, v160
	v_max_f32_e32 v227, 0, v161
	v_fma_f32 v162, -|v162|, v222, v220
	v_fma_f32 v163, -|v163|, v223, v221
	v_fma_f32 v160, -|v160|, v228, v226
	v_fma_f32 v161, -|v161|, v229, v227
	v_fma_f32 v220, |v140|, s88, 1.0
	v_fma_f32 v221, |v141|, s88, 1.0
	v_fma_f32 v226, |v164|, s88, 1.0
	v_fma_f32 v227, |v165|, s88, 1.0
	v_pk_mul_f32 v[224:225], v[140:141], v[140:141]
	v_pk_mul_f32 v[230:231], v[164:165], v[164:165]
	v_rcp_f32_e32 v220, v220
	v_rcp_f32_e32 v221, v221
	v_rcp_f32_e32 v226, v226
	v_rcp_f32_e32 v227, v227
	v_pk_mul_f32 v[224:225], v[224:225], s[72:73] op_sel_hi:[1,0]
	v_pk_mul_f32 v[230:231], v[230:231], s[72:73] op_sel_hi:[1,0]
	v_pk_fma_f32 v[222:223], v[220:221], s[90:91], v[232:233] op_sel_hi:[1,0,0]
	v_pk_fma_f32 v[228:229], v[226:227], s[90:91], v[232:233] op_sel_hi:[1,0,0]
	v_exp_f32_e32 v224, v224
	v_exp_f32_e32 v225, v225
	v_exp_f32_e32 v230, v230
	v_exp_f32_e32 v231, v231
	v_pk_fma_f32 v[222:223], v[220:221], v[222:223], s[94:95] op_sel_hi:[1,1,0]
	v_pk_fma_f32 v[228:229], v[226:227], v[228:229], s[94:95] op_sel_hi:[1,1,0]
	v_pk_fma_f32 v[222:223], v[220:221], v[222:223], s[96:97] op_sel_hi:[1,1,0]
	v_pk_fma_f32 v[228:229], v[226:227], v[228:229], s[96:97] op_sel_hi:[1,1,0]
	v_pk_fma_f32 v[222:223], v[220:221], v[222:223], s[98:99] op_sel_hi:[1,1,0]
	v_pk_fma_f32 v[228:229], v[226:227], v[228:229], s[98:99] op_sel_hi:[1,1,0]
	v_pk_mul_f32 v[222:223], v[220:221], v[222:223]
	v_pk_mul_f32 v[228:229], v[226:227], v[228:229]
	v_pk_mul_f32 v[222:223], v[224:225], v[222:223]
	v_pk_mul_f32 v[228:229], v[230:231], v[228:229]
	v_max_f32_e32 v220, 0, v140
	v_max_f32_e32 v221, 0, v141
	v_max_f32_e32 v226, 0, v164
	v_max_f32_e32 v227, 0, v165
	v_fma_f32 v140, -|v140|, v222, v220
	v_fma_f32 v141, -|v141|, v223, v221
	v_fma_f32 v164, -|v164|, v228, v226
	v_fma_f32 v165, -|v165|, v229, v227
.LBB0_160:
	v_cvt_pk_bf16_f32 v166, v162, v163
	v_cvt_pk_bf16_f32 v167, v160, v161
	v_cvt_pk_bf16_f32 v168, v140, v141
	v_cvt_pk_bf16_f32 v169, v164, v165
	v_pk_mul_f32 v[140:141], v[4:5], v[138:139] op_sel_hi:[1,0]
	v_pk_mul_f32 v[160:161], v[2:3], v[138:139] op_sel_hi:[1,0]
	v_pk_mul_f32 v[162:163], v[8:9], v[138:139] op_sel_hi:[1,0]
	s_and_b64 vcc, exec, s[6:7]
	v_pk_mul_f32 v[164:165], v[6:7], v[138:139] op_sel_hi:[1,0]
	global_store_dwordx4 v[158:159], v[166:169], off offset:64
	s_cbranch_vccnz .LBB0_162
	v_mov_b32_e32 v232, s68
	v_fma_f32 v220, |v160|, s88, 1.0
	v_fma_f32 v221, |v161|, s88, 1.0
	v_fma_f32 v226, |v140|, s88, 1.0
	v_fma_f32 v227, |v141|, s88, 1.0
	v_pk_mul_f32 v[224:225], v[160:161], v[160:161]
	v_pk_mul_f32 v[230:231], v[140:141], v[140:141]
	v_rcp_f32_e32 v220, v220
	v_rcp_f32_e32 v221, v221
	v_rcp_f32_e32 v226, v226
	v_rcp_f32_e32 v227, v227
	v_pk_mul_f32 v[224:225], v[224:225], s[72:73] op_sel_hi:[1,0]
	v_pk_mul_f32 v[230:231], v[230:231], s[72:73] op_sel_hi:[1,0]
	v_pk_fma_f32 v[222:223], v[220:221], s[90:91], v[232:233] op_sel_hi:[1,0,0]
	v_pk_fma_f32 v[228:229], v[226:227], s[90:91], v[232:233] op_sel_hi:[1,0,0]
	v_exp_f32_e32 v224, v224
	v_exp_f32_e32 v225, v225
	v_exp_f32_e32 v230, v230
	v_exp_f32_e32 v231, v231
	v_pk_fma_f32 v[222:223], v[220:221], v[222:223], s[94:95] op_sel_hi:[1,1,0]
	v_pk_fma_f32 v[228:229], v[226:227], v[228:229], s[94:95] op_sel_hi:[1,1,0]
	v_pk_fma_f32 v[222:223], v[220:221], v[222:223], s[96:97] op_sel_hi:[1,1,0]
	v_pk_fma_f32 v[228:229], v[226:227], v[228:229], s[96:97] op_sel_hi:[1,1,0]
	v_pk_fma_f32 v[222:223], v[220:221], v[222:223], s[98:99] op_sel_hi:[1,1,0]
	v_pk_fma_f32 v[228:229], v[226:227], v[228:229], s[98:99] op_sel_hi:[1,1,0]
	v_pk_mul_f32 v[222:223], v[220:221], v[222:223]
	v_pk_mul_f32 v[228:229], v[226:227], v[228:229]
	v_pk_mul_f32 v[222:223], v[224:225], v[222:223]
	v_pk_mul_f32 v[228:229], v[230:231], v[228:229]
	v_max_f32_e32 v220, 0, v160
	v_max_f32_e32 v221, 0, v161
	v_max_f32_e32 v226, 0, v140
	v_max_f32_e32 v227, 0, v141
	v_fma_f32 v160, -|v160|, v222, v220
	v_fma_f32 v161, -|v161|, v223, v221
	v_fma_f32 v140, -|v140|, v228, v226
	v_fma_f32 v141, -|v141|, v229, v227
	v_fma_f32 v220, |v164|, s88, 1.0
; __device__ __forceinline__ unsigned pk_bf16(float lo, float hi) { f32x2 v = {lo, hi}; bf16x2_t b = __builtin_convertvector(v, bf16x2_t); return __builtin_bit_cast(unsigned, b); }
; __device__ __forceinline__ f32x4 gelu4(f32x4 v) { f32x2 a = gelu_pk((f32x2){v[0], v[1]}), b = gelu_pk((f32x2){v[2], v[3]}); return (f32x4){a.x, a.y, b.x, b.y}; }
; __device__ __forceinline__ f32x2 gelu_pk(f32x2 v) {
;     const f32x2 av = __builtin_elementwise_abs(v), d = av * 0.2316418882f + 1.0f;
;     f32x2 t; t.x = __builtin_amdgcn_rcpf(d.x); t.y = __builtin_amdgcn_rcpf(d.y);
;     f32x2 q = t * 0.5307027145f + (-0.7265760135f); q = q * t + 0.7107068705f; q = q * t + (-0.142248368f); q = q * t + 0.127414796f; q = q * t;
;     const f32x2 s = (v * v) * (-0.72134752044f);
;     f32x2 e; e.x = __builtin_amdgcn_exp2f(s.x); e.y = __builtin_amdgcn_exp2f(s.y);
;     const f32x2 m = v * (q * e), r = v - m;
;     f32x2 o; o.x = v.x < 0.f ? m.x : r.x; o.y = v.y < 0.f ? m.y : r.y; return o;
;     __device__ __forceinline__ void operator()(const f32x4 (&acc)[2][2][4][2], const Unit& u, int wr, int wc, int fr, int fq, float rp0, float rp1, const f32x4& raw0, const f32x4& raw1, float& rn0, float& rn1) const {
;     ...
;                         f32x4 v0 = acc[ai][bj][m][0] * r, v1 = acc[ai][bj][m][1] * r;
;                         if (gel) { v0 = gelu4(v0); v1 = gelu4(v1); }
;                         u32x4 w; w.x = pk_bf16(v0[0], v0[1]); w.y = pk_bf16(v0[2], v0[3]); w.z = pk_bf16(v1[0], v1[1]); w.w = pk_bf16(v1[2], v1[3]);
;                         *(u32x4*)(base + (size_t)roff * ld + bj * 32) = w;
	v_fma_f32 v221, |v165|, s88, 1.0
	v_fma_f32 v226, |v162|, s88, 1.0
	v_fma_f32 v227, |v163|, s88, 1.0
	v_pk_mul_f32 v[224:225], v[164:165], v[164:165]
	v_pk_mul_f32 v[230:231], v[162:163], v[162:163]
	v_rcp_f32_e32 v220, v220
	v_rcp_f32_e32 v221, v221
	v_rcp_f32_e32 v226, v226
	v_rcp_f32_e32 v227, v227
	v_pk_mul_f32 v[224:225], v[224:225], s[72:73] op_sel_hi:[1,0]
	v_pk_mul_f32 v[230:231], v[230:231], s[72:73] op_sel_hi:[1,0]
	v_pk_fma_f32 v[222:223], v[220:221], s[90:91], v[232:233] op_sel_hi:[1,0,0]
	v_pk_fma_f32 v[228:229], v[226:227], s[90:91], v[232:233] op_sel_hi:[1,0,0]
	v_exp_f32_e32 v224, v224
	v_exp_f32_e32 v225, v225
	v_exp_f32_e32 v230, v230
	v_exp_f32_e32 v231, v231
	v_pk_fma_f32 v[222:223], v[220:221], v[222:223], s[94:95] op_sel_hi:[1,1,0]
	v_pk_fma_f32 v[228:229], v[226:227], v[228:229], s[94:95] op_sel_hi:[1,1,0]
	v_pk_fma_f32 v[222:223], v[220:221], v[222:223], s[96:97] op_sel_hi:[1,1,0]
	v_pk_fma_f32 v[228:229], v[226:227], v[228:229], s[96:97] op_sel_hi:[1,1,0]
	v_pk_fma_f32 v[222:223], v[220:221], v[222:223], s[98:99] op_sel_hi:[1,1,0]
	v_pk_fma_f32 v[228:229], v[226:227], v[228:229], s[98:99] op_sel_hi:[1,1,0]
	v_pk_mul_f32 v[222:223], v[220:221], v[222:223]
	v_pk_mul_f32 v[228:229], v[226:227], v[228:229]
	v_pk_mul_f32 v[222:223], v[224:225], v[222:223]
	v_pk_mul_f32 v[228:229], v[230:231], v[228:229]
	v_max_f32_e32 v220, 0, v164
	v_max_f32_e32 v221, 0, v165
	v_max_f32_e32 v226, 0, v162
	v_max_f32_e32 v227, 0, v163
	v_fma_f32 v164, -|v164|, v222, v220
	v_fma_f32 v165, -|v165|, v223, v221
	v_fma_f32 v162, -|v162|, v228, v226
	v_fma_f32 v163, -|v163|, v229, v227
.LBB0_162:
	s_nop 0
	v_lshl_add_u64 v[166:167], v[158:159], 0, s[76:77]
	v_cvt_pk_bf16_f32 v158, v160, v161
	v_cvt_pk_bf16_f32 v159, v140, v141
	v_cvt_pk_bf16_f32 v160, v164, v165
	v_cvt_pk_bf16_f32 v161, v162, v163
	v_mov_b32_e32 v139, v138
	global_store_dwordx4 v[166:167], v[158:161], off
	s_and_b64 vcc, exec, s[6:7]
	v_pk_mul_f32 v[162:163], v[22:23], v[138:139]
	v_mov_b32_e32 v160, v138
	v_mov_b32_e32 v161, v138
	v_pk_mul_f32 v[140:141], v[20:21], v[160:161]
	v_pk_mul_f32 v[158:159], v[18:19], v[138:139]
	v_pk_mul_f32 v[160:161], v[24:25], v[160:161]
	s_cbranch_vccnz .LBB0_164
	v_mov_b32_e32 v232, s68
	v_fma_f32 v220, |v158|, s88, 1.0
	v_fma_f32 v221, |v159|, s88, 1.0
	v_fma_f32 v226, |v140|, s88, 1.0
	v_fma_f32 v227, |v141|, s88, 1.0
	v_pk_mul_f32 v[224:225], v[158:159], v[158:159]
	v_pk_mul_f32 v[230:231], v[140:141], v[140:141]
	v_rcp_f32_e32 v220, v220
	v_rcp_f32_e32 v221, v221
	v_rcp_f32_e32 v226, v226
	v_rcp_f32_e32 v227, v227
	v_pk_mul_f32 v[224:225], v[224:225], s[72:73] op_sel_hi:[1,0]
	v_pk_mul_f32 v[230:231], v[230:231], s[72:73] op_sel_hi:[1,0]
	v_pk_fma_f32 v[222:223], v[220:221], s[90:91], v[232:233] op_sel_hi:[1,0,0]
	v_pk_fma_f32 v[228:229], v[226:227], s[90:91], v[232:233] op_sel_hi:[1,0,0]
	v_exp_f32_e32 v224, v224
	v_exp_f32_e32 v225, v225
	v_exp_f32_e32 v230, v230
	v_exp_f32_e32 v231, v231
	v_pk_fma_f32 v[222:223], v[220:221], v[222:223], s[94:95] op_sel_hi:[1,1,0]
	v_pk_fma_f32 v[228:229], v[226:227], v[228:229], s[94:95] op_sel_hi:[1,1,0]
	v_pk_fma_f32 v[222:223], v[220:221], v[222:223], s[96:97] op_sel_hi:[1,1,0]
	v_pk_fma_f32 v[228:229], v[226:227], v[228:229], s[96:97] op_sel_hi:[1,1,0]
	v_pk_fma_f32 v[222:223], v[220:221], v[222:223], s[98:99] op_sel_hi:[1,1,0]
	v_pk_fma_f32 v[228:229], v[226:227], v[228:229], s[98:99] op_sel_hi:[1,1,0]
	v_pk_mul_f32 v[222:223], v[220:221], v[222:223]
	v_pk_mul_f32 v[228:229], v[226:227], v[228:229]
	v_pk_mul_f32 v[222:223], v[224:225], v[222:223]
	v_pk_mul_f32 v[228:229], v[230:231], v[228:229]
	v_max_f32_e32 v220, 0, v158
	v_max_f32_e32 v221, 0, v159
	v_max_f32_e32 v226, 0, v140
	v_max_f32_e32 v227, 0, v141
	v_fma_f32 v158, -|v158|, v222, v220
	v_fma_f32 v159, -|v159|, v223, v221
	v_fma_f32 v140, -|v140|, v228, v226
	v_fma_f32 v141, -|v141|, v229, v227
	v_fma_f32 v220, |v162|, s88, 1.0
	v_fma_f32 v221, |v163|, s88, 1.0
	v_fma_f32 v226, |v160|, s88, 1.0
	v_fma_f32 v227, |v161|, s88, 1.0
	v_pk_mul_f32 v[224:225], v[162:163], v[162:163]
	v_pk_mul_f32 v[230:231], v[160:161], v[160:161]
	v_rcp_f32_e32 v220, v220
	v_rcp_f32_e32 v221, v221
	v_rcp_f32_e32 v226, v226
	v_rcp_f32_e32 v227, v227
	v_pk_mul_f32 v[224:225], v[224:225], s[72:73] op_sel_hi:[1,0]
	v_pk_mul_f32 v[230:231], v[230:231], s[72:73] op_sel_hi:[1,0]
	v_pk_fma_f32 v[222:223], v[220:221], s[90:91], v[232:233] op_sel_hi:[1,0,0]
	v_pk_fma_f32 v[228:229], v[226:227], s[90:91], v[232:233] op_sel_hi:[1,0,0]
	v_exp_f32_e32 v224, v224
	v_exp_f32_e32 v225, v225
	v_exp_f32_e32 v230, v230
	v_exp_f32_e32 v231, v231
	v_pk_fma_f32 v[222:223], v[220:221], v[222:223], s[94:95] op_sel_hi:[1,1,0]
	v_pk_fma_f32 v[228:229], v[226:227], v[228:229], s[94:95] op_sel_hi:[1,1,0]
	v_pk_fma_f32 v[222:223], v[220:221], v[222:223], s[96:97] op_sel_hi:[1,1,0]
	v_pk_fma_f32 v[228:229], v[226:227], v[228:229], s[96:97] op_sel_hi:[1,1,0]
	v_pk_fma_f32 v[222:223], v[220:221], v[222:223], s[98:99] op_sel_hi:[1,1,0]
	v_pk_fma_f32 v[228:229], v[226:227], v[228:229], s[98:99] op_sel_hi:[1,1,0]
	v_pk_mul_f32 v[222:223], v[220:221], v[222:223]
	v_pk_mul_f32 v[228:229], v[226:227], v[228:229]
	v_pk_mul_f32 v[222:223], v[224:225], v[222:223]
	v_pk_mul_f32 v[228:229], v[230:231], v[228:229]
	v_max_f32_e32 v220, 0, v162
	v_max_f32_e32 v221, 0, v163
	v_max_f32_e32 v226, 0, v160
	v_max_f32_e32 v227, 0, v161
	v_fma_f32 v162, -|v162|, v222, v220
	v_fma_f32 v163, -|v163|, v223, v221
	v_fma_f32 v160, -|v160|, v228, v226
	v_fma_f32 v161, -|v161|, v229, v227
